# row-norm loops: gain vectors loaded once per wave instead of per row, per-load drains removed
# speedup vs baseline: 1.0133x; 1.0133x over previous
; DI unsigned pk2(float lo, float hi) { f32x2_t v = {lo, hi}; bf16x2_t b = __builtin_convertvector(v, bf16x2_t); return __builtin_bit_cast(unsigned, b); }
; DI void norm_rows(const float* src, int nrows, const float* g, bf16* dst, int gw, int NGW, int lane) {
;     int row = gw; if (row >= nrows) return;
;     f32x4 v[8], vn[8];
;     { const f32x4* xr = (const f32x4*)(src + (size_t)row * DM) + lane;
; #pragma unroll
;       for (int j = 0; j < 8; ++j) v[j] = __builtin_nontemporal_load(xr + 64 * j); }
;     for (;;) {
;         const int nrow = row + NGW; const bool has = nrow < nrows;
;         if (has) { const f32x4* xr = (const f32x4*)(src + (size_t)nrow * DM) + lane;
; #pragma unroll
;             for (int j = 0; j < 8; ++j) vn[j] = __builtin_nontemporal_load(xr + 64 * j); }
;         float ss = 0.f;
; #pragma unroll
;         for (int j = 0; j < 8; ++j) ss += (v[j].x * v[j].x + v[j].y * v[j].y) + (v[j].z * v[j].z + v[j].w * v[j].w);
;         const float r = rsqrtf(wave_sum(ss) * (1.f / DM) + EPS);
;         u32x2* o = (u32x2*)(dst + (size_t)row * DM) + lane;
; #pragma unroll
;         for (int j = 0; j < 8; ++j) { const f32x4 gg = ((const f32x4*)g)[lane + 64 * j]; u32x2 w; w.x = pk2(v[j].x * r * gg.x, v[j].y * r * gg.y); w.y = pk2(v[j].z * r * gg.z, v[j].w * r * gg.w); o[64 * j] = w; }
.LBB0_61:
	s_or_b64 exec, exec, s[4:5]
	s_cmpk_gt_i32 s8, 0x3fff
	s_cbranch_scc1 .LBB0_68
	s_ashr_i32 s9, s8, 31
	s_lshl_b64 s[0:1], s[8:9], 13
	v_readlane_b32 s36, v252, 4
	v_readlane_b32 s37, v252, 5
	s_add_u32 s0, s36, s0
	s_addc_u32 s1, s37, s1
	v_lshlrev_b32_e32 v16, 4, v15
	v_mov_b32_e32 v17, 0
	v_lshl_add_u64 v[2:3], s[0:1], 0, v[16:17]
	v_add_co_u32_e32 v2, vcc, 0x1000, v2
	global_load_dwordx4 v[62:65], v16, s[0:1] nt
	global_load_dwordx4 v[58:61], v16, s[0:1] offset:1024 nt
	global_load_dwordx4 v[54:57], v16, s[0:1] offset:2048 nt
	global_load_dwordx4 v[50:53], v16, s[0:1] offset:3072 nt
	v_addc_co_u32_e32 v3, vcc, 0, v3, vcc
	global_load_dwordx4 v[46:49], v[2:3], off nt
	global_load_dwordx4 v[10:13], v[2:3], off offset:1024 nt
	global_load_dwordx4 v[6:9], v[2:3], off offset:2048 nt
	s_nop 0
	global_load_dwordx4 v[2:5], v[2:3], off offset:3072 nt
	v_readlane_b32 s38, v252, 6
	v_readlane_b32 s39, v252, 7
	v_readlane_b32 s40, v252, 8
	v_readlane_b32 s41, v252, 9
	v_readlane_b32 s42, v252, 10
	v_readlane_b32 s43, v252, 11
	v_readlane_b32 s44, v252, 12
	v_readlane_b32 s45, v252, 13
	v_readlane_b32 s46, v252, 14
	v_readlane_b32 s47, v252, 15
	v_readlane_b32 s48, v252, 16
	v_readlane_b32 s49, v252, 17
	v_readlane_b32 s50, v252, 18
	v_readlane_b32 s51, v252, 19
	v_lshl_add_u64 v[66:67], s[36:37], 0, v[16:17]
	v_readlane_b32 s36, v252, 20
	v_readlane_b32 s38, v252, 22
	v_readlane_b32 s39, v252, 23
	s_mov_b64 s[0:1], 0x1000
	v_readlane_b32 s3, v252, 36
	v_lshl_add_u64 v[68:69], s[38:39], 0, v[16:17]
	v_lshl_add_u64 v[70:71], v[68:69], 0, s[0:1]
	s_mov_b64 s[0:1], 0x1400
	v_lshl_add_u64 v[72:73], v[68:69], 0, s[0:1]
	s_mov_b64 s[0:1], 0x1800
	v_lshl_add_u64 v[74:75], v[68:69], 0, s[0:1]
	s_mov_b64 s[0:1], 0x1c00
	v_lshl_add_u64 v[76:77], v[68:69], 0, s[0:1]
	s_add_i32 s0, s8, s64
	s_ashr_i32 s1, s17, 31
	s_ashr_i32 s5, s3, 31
	s_add_u32 s4, s17, s3
	s_addc_u32 s5, s1, s5
	s_lshl_b64 s[4:5], s[4:5], 12
	s_add_u32 s1, s6, s4
	v_readlane_b32 s8, v252, 0
	s_addc_u32 s5, s7, s5
	v_readlane_b32 s10, v252, 2
	v_readlane_b32 s11, v252, 3
	s_add_u32 s4, s10, s1
	v_mov_b32_e32 v15, v17
	s_addc_u32 s5, s11, s5
	s_mov_b32 s12, s64
	v_lshl_add_u64 v[14:15], s[4:5], 0, v[14:15]
	s_mov_b64 s[4:5], 0x7000800
	s_ashr_i32 s13, s64, 31
	v_lshl_add_u64 v[78:79], v[14:15], 0, s[4:5]
	s_lshl_b64 s[4:5], s[12:13], 12
	v_mov_b32_e32 v80, 0x358637bd
	s_mov_b32 s8, 0x800000
	v_readlane_b32 s37, v252, 21
	v_readlane_b32 s40, v252, 24
	v_readlane_b32 s41, v252, 25
	v_readlane_b32 s42, v252, 26
	v_readlane_b32 s43, v252, 27
	v_readlane_b32 s44, v252, 28
	v_readlane_b32 s45, v252, 29
	v_readlane_b32 s46, v252, 30
	v_readlane_b32 s47, v252, 31
	v_readlane_b32 s48, v252, 32
	v_readlane_b32 s49, v252, 33
	v_readlane_b32 s50, v252, 34
	v_readlane_b32 s51, v252, 35
	v_readlane_b32 s9, v252, 1
	global_load_dwordx4 v[180:183], v[68:69], off
	global_load_dwordx4 v[184:187], v[68:69], off offset:1024
	global_load_dwordx4 v[188:191], v[68:69], off offset:2048
	global_load_dwordx4 v[192:195], v[68:69], off offset:3072
	global_load_dwordx4 v[196:199], v[70:71], off
	global_load_dwordx4 v[208:211], v[72:73], off
	global_load_dwordx4 v[212:215], v[74:75], off
	global_load_dwordx4 v[216:219], v[76:77], off
	s_waitcnt vmcnt(0)
	s_branch .LBB0_64

; DI unsigned pk2(float lo, float hi) { f32x2_t v = {lo, hi}; bf16x2_t b = __builtin_convertvector(v, bf16x2_t); return __builtin_bit_cast(unsigned, b); }
; DI void norm_rows(const float* src, int nrows, const float* g, bf16* dst, int gw, int NGW, int lane) {
;     ...
;         float ss = 0.f;
; #pragma unroll
;         for (int j = 0; j < 8; ++j) ss += (v[j].x * v[j].x + v[j].y * v[j].y) + (v[j].z * v[j].z + v[j].w * v[j].w);
;         const float r = rsqrtf(wave_sum(ss) * (1.f / DM) + EPS);
;         u32x2* o = (u32x2*)(dst + (size_t)row * DM) + lane;
; #pragma unroll
;         for (int j = 0; j < 8; ++j) { const f32x4 gg = ((const f32x4*)g)[lane + 64 * j]; u32x2 w; w.x = pk2(v[j].x * r * gg.x, v[j].y * r * gg.y); w.y = pk2(v[j].z * r * gg.z, v[j].w * r * gg.w); o[64 * j] = w; }
.LBB0_66:
	v_pk_mul_f32 v[94:95], v[62:63], v[62:63]
	v_pk_mul_f32 v[96:97], v[58:59], v[58:59]
	v_pk_mul_f32 v[90:91], v[64:65], v[64:65]
	v_pk_mul_f32 v[92:93], v[60:61], v[60:61]
	v_mov_b32_e32 v98, v94
	v_mov_b32_e32 v99, v96
	v_mov_b32_e32 v96, v95
	v_pk_mul_f32 v[86:87], v[56:57], v[56:57]
	v_pk_mul_f32 v[88:89], v[54:55], v[54:55]
	v_pk_add_f32 v[94:95], v[98:99], v[96:97]
	v_mov_b32_e32 v96, v90
	v_mov_b32_e32 v97, v92
	v_mov_b32_e32 v92, v91
	v_pk_add_f32 v[90:91], v[96:97], v[92:93]
	v_pk_mov_b32 v[92:93], v[88:89], v[86:87] op_sel:[1,0]
	v_mov_b32_e32 v89, v87
	v_pk_add_f32 v[86:87], v[92:93], v[88:89]
	v_pk_add_f32 v[90:91], v[94:95], v[90:91]
	v_pk_add_f32 v[86:87], v[86:87], v[86:87] op_sel_hi:[0,1]
	v_mul_f32_e32 v86, v50, v50
	v_pk_fma_f32 v[88:89], v[50:51], v[50:51], v[86:87] op_sel_hi:[1,1,0]
	v_mul_f32_e32 v86, v52, v52
	v_pk_add_f32 v[90:91], v[90:91], v[90:91] op_sel_hi:[0,1]
	v_pk_fma_f32 v[92:93], v[52:53], v[52:53], v[86:87] op_sel_hi:[1,1,0]
	v_mul_f32_e32 v88, v46, v46
	v_mul_f32_e32 v92, v47, v47
	v_mul_f32_e32 v86, v48, v48
	v_mul_f32_e32 v90, v49, v49
	v_pk_mul_f32 v[82:83], v[12:13], v[12:13]
	v_pk_mul_f32 v[84:85], v[10:11], v[10:11]
	v_pk_add_f32 v[88:89], v[88:89], v[92:93]
	v_pk_add_f32 v[86:87], v[86:87], v[90:91]
	s_mov_b32 s1, -1
	v_pk_add_f32 v[86:87], v[88:89], v[86:87]
	v_pk_mov_b32 v[88:89], v[84:85], v[82:83] op_sel:[1,0]
	v_mov_b32_e32 v85, v83
	v_pk_add_f32 v[82:83], v[88:89], v[84:85]
	s_mov_b32 s9, -1
	v_pk_add_f32 v[88:89], v[82:83], v[82:83] op_sel_hi:[0,1]
	v_mul_f32_e32 v82, v6, v6
	v_pk_fma_f32 v[90:91], v[6:7], v[6:7], v[82:83] op_sel_hi:[1,1,0]
	v_mul_f32_e32 v82, v8, v8
	s_mov_b32 s10, -1
	s_mov_b32 s11, -1
	s_mov_b32 s12, -1
	s_mov_b32 s13, -1
	v_pk_fma_f32 v[92:93], v[8:9], v[8:9], v[82:83] op_sel_hi:[1,1,0]
	v_pk_add_f32 v[86:87], v[86:87], v[86:87] op_sel_hi:[0,1]
	v_mul_f32_e32 v90, v2, v2
	v_mul_f32_e32 v92, v3, v3
	v_mul_f32_e32 v88, v4, v4
	v_mul_f32_e32 v86, v5, v5
	v_pk_add_f32 v[90:91], v[90:91], v[92:93]
	v_pk_add_f32 v[86:87], v[88:89], v[86:87]
	s_nop 0
	v_pk_add_f32 v[86:87], v[90:91], v[86:87]
	s_nop 0
	v_add_f32_e32 v81, v86, v87
	v_mbcnt_lo_u32_b32 v86, s1, 0
	v_mbcnt_hi_u32_b32 v86, s1, v86
	v_lshlrev_b32_e32 v86, 2, v86
	v_xor_b32_e32 v86, 4, v86
	ds_bpermute_b32 v86, v86, v81
	s_waitcnt lgkmcnt(0)
	v_add_f32_e32 v81, v81, v86
	v_mbcnt_lo_u32_b32 v86, s9, 0
	v_mbcnt_hi_u32_b32 v86, s9, v86
	v_lshlrev_b32_e32 v86, 2, v86
	v_xor_b32_e32 v86, 8, v86
	ds_bpermute_b32 v86, v86, v81
	s_waitcnt lgkmcnt(0)
	v_add_f32_e32 v81, v81, v86
	v_mbcnt_lo_u32_b32 v86, s10, 0
	v_mbcnt_hi_u32_b32 v86, s10, v86
	v_lshlrev_b32_e32 v86, 2, v86
	v_xor_b32_e32 v86, 16, v86
	ds_bpermute_b32 v86, v86, v81
	s_waitcnt lgkmcnt(0)
	v_add_f32_e32 v81, v81, v86
	v_mbcnt_lo_u32_b32 v86, s11, 0
	v_mbcnt_hi_u32_b32 v86, s11, v86
	v_lshlrev_b32_e32 v86, 2, v86
	v_xor_b32_e32 v86, 32, v86
	ds_bpermute_b32 v86, v86, v81
	s_waitcnt lgkmcnt(0)
	v_add_f32_e32 v81, v81, v86
	v_mbcnt_lo_u32_b32 v86, s12, 0
	v_mbcnt_hi_u32_b32 v86, s12, v86
	v_lshlrev_b32_e32 v86, 2, v86
	v_xor_b32_e32 v86, 64, v86
	ds_bpermute_b32 v86, v86, v81
	s_waitcnt lgkmcnt(0)
	v_add_f32_e32 v81, v81, v86
	v_mbcnt_lo_u32_b32 v86, s13, 0
	v_mbcnt_hi_u32_b32 v86, s13, v86
	v_lshlrev_b32_e32 v86, 2, v86
	v_xor_b32_e32 v86, 0x80, v86
	ds_bpermute_b32 v86, v86, v81
	s_waitcnt lgkmcnt(0)
	v_add_f32_e32 v81, v81, v86
	v_fmamk_f32 v81, v81, 0x3a000000, v80
	v_mul_f32_e32 v86, 0x4b800000, v81
	v_cmp_gt_f32_e32 vcc, s8, v81
	s_nop 1
	v_cndmask_b32_e32 v81, v81, v86, vcc
	v_rsq_f32_e32 v81, v81
	s_nop 0
	v_mul_f32_e32 v86, 0x45800000, v81
	v_cndmask_b32_e32 v86, v81, v86, vcc
	v_pk_mul_f32 v[62:63], v[62:63], v[86:87] op_sel_hi:[1,0]
	v_pk_mul_f32 v[64:65], v[64:65], v[86:87] op_sel_hi:[1,0]
	v_pk_mul_f32 v[62:63], v[180:181], v[62:63]
	v_pk_mul_f32 v[64:65], v[182:183], v[64:65]
	v_cvt_pk_bf16_f32 v62, v62, v63
	v_cvt_pk_bf16_f32 v63, v64, v65
	global_store_dwordx2 v[78:79], v[62:63], off offset:-2048
	v_pk_mul_f32 v[58:59], v[58:59], v[86:87] op_sel_hi:[1,0]
	v_pk_mul_f32 v[60:61], v[60:61], v[86:87] op_sel_hi:[1,0]
	v_pk_mul_f32 v[54:55], v[54:55], v[86:87] op_sel_hi:[1,0]
	v_pk_mul_f32 v[56:57], v[56:57], v[86:87] op_sel_hi:[1,0]
	v_pk_mul_f32 v[50:51], v[50:51], v[86:87] op_sel_hi:[1,0]
	v_pk_mul_f32 v[52:53], v[52:53], v[86:87] op_sel_hi:[1,0]
	v_pk_mul_f32 v[46:47], v[46:47], v[86:87] op_sel_hi:[1,0]
	v_pk_mul_f32 v[48:49], v[48:49], v[86:87] op_sel_hi:[1,0]
	v_pk_mul_f32 v[10:11], v[10:11], v[86:87] op_sel_hi:[1,0]
	v_pk_mul_f32 v[12:13], v[12:13], v[86:87] op_sel_hi:[1,0]
	v_pk_mul_f32 v[6:7], v[6:7], v[86:87] op_sel_hi:[1,0]
	v_pk_mul_f32 v[8:9], v[8:9], v[86:87] op_sel_hi:[1,0]
	v_pk_mul_f32 v[2:3], v[2:3], v[86:87] op_sel_hi:[1,0]
	v_pk_mul_f32 v[4:5], v[4:5], v[86:87] op_sel_hi:[1,0]
	s_andn2_b64 vcc, exec, s[6:7]
	s_mov_b64 s[6:7], -1
	v_pk_mul_f32 v[58:59], v[184:185], v[58:59]
	v_pk_mul_f32 v[60:61], v[186:187], v[60:61]
	v_cvt_pk_bf16_f32 v58, v58, v59
	v_cvt_pk_bf16_f32 v59, v60, v61
	global_store_dwordx2 v[78:79], v[58:59], off offset:-1536
	v_pk_mul_f32 v[54:55], v[188:189], v[54:55]
	v_pk_mul_f32 v[56:57], v[190:191], v[56:57]
	v_cvt_pk_bf16_f32 v54, v54, v55
	v_cvt_pk_bf16_f32 v55, v56, v57
	global_store_dwordx2 v[78:79], v[54:55], off offset:-1024
	v_pk_mul_f32 v[50:51], v[192:193], v[50:51]
	v_pk_mul_f32 v[52:53], v[194:195], v[52:53]
	v_cvt_pk_bf16_f32 v50, v50, v51
	v_cvt_pk_bf16_f32 v51, v52, v53
	global_store_dwordx2 v[78:79], v[50:51], off offset:-512
	v_pk_mul_f32 v[46:47], v[46:47], v[196:197]
	v_pk_mul_f32 v[48:49], v[48:49], v[198:199]
	v_cvt_pk_bf16_f32 v46, v46, v47
	v_cvt_pk_bf16_f32 v47, v48, v49
	global_store_dwordx2 v[78:79], v[46:47], off
	v_pk_mul_f32 v[10:11], v[10:11], v[208:209]
	v_pk_mul_f32 v[12:13], v[12:13], v[210:211]
	v_cvt_pk_bf16_f32 v10, v10, v11
	v_cvt_pk_bf16_f32 v11, v12, v13
	global_store_dwordx2 v[78:79], v[10:11], off offset:512
	v_pk_mul_f32 v[6:7], v[6:7], v[212:213]
	v_pk_mul_f32 v[8:9], v[8:9], v[214:215]
	v_cvt_pk_bf16_f32 v6, v6, v7
	v_cvt_pk_bf16_f32 v7, v8, v9
	global_store_dwordx2 v[78:79], v[6:7], off offset:1024
	v_pk_mul_f32 v[2:3], v[2:3], v[216:217]
	v_pk_mul_f32 v[4:5], v[4:5], v[218:219]
	v_cvt_pk_bf16_f32 v2, v2, v3
	v_cvt_pk_bf16_f32 v3, v4, v5
	global_store_dwordx2 v[78:79], v[2:3], off offset:1536
	s_cbranch_vccnz .LBB0_63
; DI void norm_rows(const float* src, int nrows, const float* g, bf16* dst, int gw, int NGW, int lane) {
;     ...
;         if (!has) break;
; #pragma unroll
;         for (int j = 0; j < 8; ++j) v[j] = vn[j];
;         row = nrow;
	s_waitcnt vmcnt(8)
	s_add_i32 s0, s0, s64
	v_lshl_add_u64 v[78:79], v[78:79], 0, s[4:5]
	s_mov_b64 s[6:7], 0
	v_mov_b32_e32 v5, v33
	v_mov_b32_e32 v4, v32
	v_mov_b32_e32 v3, v31
	v_mov_b32_e32 v2, v30
	v_mov_b32_e32 v9, v37
	v_mov_b32_e32 v8, v36
	v_mov_b32_e32 v7, v35
	v_mov_b32_e32 v6, v34
	v_mov_b32_e32 v13, v41
	v_mov_b32_e32 v12, v40
	v_mov_b32_e32 v11, v39
	v_mov_b32_e32 v10, v38
	v_mov_b32_e32 v49, v45
	v_mov_b32_e32 v48, v44
	v_mov_b32_e32 v47, v43
	v_mov_b32_e32 v46, v42
	v_mov_b32_e32 v53, v17
	v_mov_b32_e32 v52, v16
	v_mov_b32_e32 v51, v15
	v_mov_b32_e32 v50, v14
	v_mov_b32_e32 v57, v21
	v_mov_b32_e32 v56, v20
	v_mov_b32_e32 v55, v19
	v_mov_b32_e32 v54, v18
	v_mov_b32_e32 v61, v25
	v_mov_b32_e32 v60, v24
	v_mov_b32_e32 v59, v23
	v_mov_b32_e32 v58, v22
	v_mov_b32_e32 v65, v29
	v_mov_b32_e32 v64, v28
	v_mov_b32_e32 v63, v27
	v_mov_b32_e32 v62, v26
	s_branch .LBB0_63

; DI unsigned pk2(float lo, float hi) { f32x2_t v = {lo, hi}; bf16x2_t b = __builtin_convertvector(v, bf16x2_t); return __builtin_bit_cast(unsigned, b); }
; DI void resnorm_rows(const float* Y, const float* Xs, float* Xd, const float* gpost, const float* gpre, bf16* H, int gw, int NGW, int lane) {
;     int row = gw; if (row >= T) return;
;     f32x4 y[8], x[8], yn[8], xn[8];
;     { const f32x4* yr = (const f32x4*)(Y + (size_t)row * DM) + lane; const f32x4* xr = (const f32x4*)(Xs + (size_t)row * DM) + lane;
; #pragma unroll
;       for (int j = 0; j < 8; ++j) { y[j] = __builtin_nontemporal_load(yr + 64 * j); x[j] = __builtin_nontemporal_load(xr + 64 * j); } }
;     for (;;) {
;         const int nrow = row + NGW; const bool has = nrow < T;
;         if (has) { const f32x4* yr = (const f32x4*)(Y + (size_t)nrow * DM) + lane; const f32x4* xr = (const f32x4*)(Xs + (size_t)nrow * DM) + lane;
; #pragma unroll
;             for (int j = 0; j < 8; ++j) { yn[j] = __builtin_nontemporal_load(yr + 64 * j); xn[j] = __builtin_nontemporal_load(xr + 64 * j); } }
;     ...
;         for (int j = 0; j < 8; ++j) { const f32x4 gg = ((const f32x4*)gpost)[lane + 64 * j]; x[j] = x[j] + y[j] * r * gg; __builtin_nontemporal_store(x[j], xo + 64 * j);
;             s2 += (x[j].x * x[j].x + x[j].y * x[j].y) + (x[j].z * x[j].z + x[j].w * x[j].w); }
;         if (H) {
;             const float r2 = rsqrtf(wave_sum(s2) * (1.f / DM) + EPS);
;             u32x2* o = (u32x2*)(H + (size_t)row * DM) + lane;
; #pragma unroll
;             for (int j = 0; j < 8; ++j) { const f32x4 gg = ((const f32x4*)gpre)[lane + 64 * j]; u32x2 w; w.x = pk2(x[j].x * r2 * gg.x, x[j].y * r2 * gg.y); w.y = pk2(x[j].z * r2 * gg.z, x[j].w * r2 * gg.w); o[64 * j] = w; }
.LBB0_478:
	s_or_b64 exec, exec, s[0:1]
	s_mov_b32 s0, -1
	s_waitcnt lgkmcnt(0)
	s_barrier
	s_lshl_b32 s10, s46, 11
	v_mbcnt_lo_u32_b32 v0, s0, 0
	v_mbcnt_hi_u32_b32 v0, s0, v0
	v_add_u32_e32 v0, s68, v0
	s_mov_b64 s[0:1], 0
	s_mov_b32 s11, s37
	v_readfirstlane_b32 s8, v0
	s_ashr_i32 s18, s8, 6
	v_readlane_b32 s8, v252, 36
	v_and_b32_e32 v1, 63, v0
	s_add_i32 s8, s18, s8
	s_cmpk_gt_i32 s8, 0x3fff
	v_lshlrev_b32_e32 v160, 4, v1
	v_lshlrev_b32_e32 v128, 3, v1
	s_cbranch_scc1 .LBB0_485
	v_readlane_b32 s20, v252, 0
	v_readlane_b32 s40, v252, 20
	v_readlane_b32 s22, v252, 2
	v_readlane_b32 s41, v252, 21
	v_readlane_b32 s42, v252, 22
	v_readlane_b32 s43, v252, 23
	v_readlane_b32 s44, v252, 24
	v_readlane_b32 s45, v252, 25
	v_readlane_b32 s46, v252, 26
	v_readlane_b32 s47, v252, 27
	v_readlane_b32 s48, v252, 28
	v_readlane_b32 s49, v252, 29
	v_readlane_b32 s50, v252, 30
	v_readlane_b32 s51, v252, 31
	v_readlane_b32 s23, v252, 3
	s_add_u32 s9, s22, s0
	v_readlane_b32 s52, v252, 32
	v_readlane_b32 s53, v252, 33
	v_readlane_b32 s54, v252, 34
	v_readlane_b32 s55, v252, 35
	s_mov_b64 s[40:41], s[44:45]
	s_addc_u32 s19, s23, s1
	s_lshl_b64 s[12:13], s[10:11], 2
	s_mov_b64 s[42:43], s[46:47]
	s_add_u32 s14, s42, s12
	s_addc_u32 s15, s43, s13
	s_mov_b64 s[44:45], s[48:49]
	s_mov_b64 s[46:47], s[50:51]
	s_mov_b64 s[48:49], s[52:53]
	s_mov_b64 s[50:51], s[54:55]
	s_add_u32 s12, s40, s12
	v_readlane_b32 s16, v255, 7
	s_addc_u32 s13, s41, s13
	v_readlane_b32 s17, v255, 8
	v_readlane_b32 s40, v252, 4
	v_readlane_b32 s21, v252, 1
	s_and_b64 s[16:17], s[16:17], exec
	v_readlane_b32 s41, v252, 5
	s_cselect_b32 s17, s41, s21
	s_cselect_b32 s16, s40, s20
	s_add_u32 s20, s9, 0x17000000
	s_addc_u32 s21, s19, 0
	s_ashr_i32 s9, s8, 31
	s_lshl_b64 s[22:23], s[8:9], 13
	s_add_u32 s24, s20, s22
	s_addc_u32 s25, s21, s23
	v_lshl_add_u64 v[0:1], s[24:25], 0, v[160:161]
	s_add_u32 s22, s16, s22
	s_movk_i32 s9, 0x1000
	s_addc_u32 s23, s17, s23
	v_add_co_u32_e32 v0, vcc, s9, v0
	v_lshl_add_u64 v[2:3], s[22:23], 0, v[160:161]
	s_nop 0
	v_addc_co_u32_e32 v1, vcc, 0, v1, vcc
	v_add_co_u32_e32 v2, vcc, s9, v2
	global_load_dwordx4 v[124:127], v160, s[24:25] nt
	global_load_dwordx4 v[120:123], v160, s[24:25] offset:1024 nt
	global_load_dwordx4 v[92:95], v160, s[22:23] nt
	global_load_dwordx4 v[88:91], v160, s[22:23] offset:1024 nt
	global_load_dwordx4 v[116:119], v160, s[24:25] offset:2048 nt
	global_load_dwordx4 v[112:115], v160, s[24:25] offset:3072 nt
	global_load_dwordx4 v[84:87], v160, s[22:23] offset:2048 nt
	global_load_dwordx4 v[80:83], v160, s[22:23] offset:3072 nt
	v_addc_co_u32_e32 v3, vcc, 0, v3, vcc
	global_load_dwordx4 v[108:111], v[0:1], off nt
	global_load_dwordx4 v[104:107], v[0:1], off offset:1024 nt
	global_load_dwordx4 v[76:79], v[2:3], off nt
	global_load_dwordx4 v[72:75], v[2:3], off offset:1024 nt
	global_load_dwordx4 v[100:103], v[0:1], off offset:2048 nt
	global_load_dwordx4 v[96:99], v[0:1], off offset:3072 nt
	global_load_dwordx4 v[68:71], v[2:3], off offset:2048 nt
	global_load_dwordx4 v[64:67], v[2:3], off offset:3072 nt
	v_or_b32_e32 v0, 0x1000, v160
	v_mov_b32_e32 v1, v161
	v_or_b32_e32 v2, 0x1400, v160
	v_mov_b32_e32 v3, v161
	v_or_b32_e32 v4, 0x1800, v160
	v_mov_b32_e32 v5, v161
	v_or_b32_e32 v6, 0x1c00, v160
	v_mov_b32_e32 v7, v161
	v_lshl_add_u64 v[134:135], s[12:13], 0, v[160:161]
	v_lshl_add_u64 v[136:137], s[12:13], 0, v[0:1]
	v_lshl_add_u64 v[138:139], s[12:13], 0, v[2:3]
	v_lshl_add_u64 v[140:141], s[12:13], 0, v[4:5]
	v_lshl_add_u64 v[142:143], s[12:13], 0, v[6:7]
	s_ashr_i32 s9, s18, 31
	v_readlane_b32 s12, v252, 36
	v_lshl_add_u64 v[144:145], s[14:15], 0, v[160:161]
	v_lshl_add_u64 v[146:147], s[14:15], 0, v[0:1]
	v_lshl_add_u64 v[148:149], s[14:15], 0, v[2:3]
	v_lshl_add_u64 v[150:151], s[14:15], 0, v[4:5]
	v_lshl_add_u64 v[152:153], s[14:15], 0, v[6:7]
	s_add_u32 s14, s12, s18
	v_readlane_b32 s12, v254, 48
	s_addc_u32 s15, s12, s9
	s_lshl_b64 s[12:13], s[14:15], 13
	v_readlane_b32 s9, v254, 44
	s_add_u32 s12, s9, s12
	v_readlane_b32 s9, v254, 45
	s_addc_u32 s13, s9, s13
	v_readlane_b32 s9, v254, 49
	v_lshl_add_u64 v[154:155], s[12:13], 0, v[160:161]
	s_add_i32 s12, s9, s18
	s_lshl_b64 s[14:15], s[14:15], 12
	s_add_u32 s9, s0, s14
	s_addc_u32 s13, s1, s15
	v_readlane_b32 s14, v254, 52
	v_readlane_b32 s15, v254, 53
	s_add_u32 s14, s14, s9
	v_mov_b32_e32 v129, v161
	s_addc_u32 s15, s15, s13
	v_lshl_add_u64 v[130:131], s[20:21], 0, v[160:161]
	v_lshl_add_u64 v[132:133], s[16:17], 0, v[160:161]
	v_lshl_add_u64 v[156:157], s[14:15], 0, v[128:129]
	v_readlane_b32 s42, v252, 6
	v_readlane_b32 s43, v252, 7
	v_readlane_b32 s44, v252, 8
	v_readlane_b32 s45, v252, 9
	v_readlane_b32 s46, v252, 10
	v_readlane_b32 s47, v252, 11
	v_readlane_b32 s48, v252, 12
	v_readlane_b32 s49, v252, 13
	v_readlane_b32 s50, v252, 14
	v_readlane_b32 s51, v252, 15
	v_readlane_b32 s52, v252, 16
	v_readlane_b32 s53, v252, 17
	v_readlane_b32 s54, v252, 18
	v_readlane_b32 s55, v252, 19
	global_load_dwordx4 v[180:183], v[134:135], off
	global_load_dwordx4 v[184:187], v[134:135], off offset:1024
	global_load_dwordx4 v[188:191], v[134:135], off offset:2048
	global_load_dwordx4 v[192:195], v[134:135], off offset:3072
	global_load_dwordx4 v[196:199], v[136:137], off
	global_load_dwordx4 v[208:211], v[138:139], off
	global_load_dwordx4 v[212:215], v[140:141], off
	global_load_dwordx4 v[216:219], v[142:143], off
	global_load_dwordx4 v[220:223], v[144:145], off
	global_load_dwordx4 v[224:227], v[144:145], off offset:1024
	global_load_dwordx4 v[228:231], v[144:145], off offset:2048
	global_load_dwordx4 v[232:235], v[144:145], off offset:3072
	global_load_dwordx4 v[236:239], v[146:147], off
	global_load_dwordx4 v[240:243], v[148:149], off
	global_load_dwordx4 v[244:247], v[150:151], off
	global_load_dwordx4 v[248:251], v[152:153], off
	s_waitcnt vmcnt(0)
	s_branch .LBB0_481

; DI void resnorm_rows(const float* Y, const float* Xs, float* Xd, const float* gpost, const float* gpre, bf16* H, int gw, int NGW, int lane) {
;     ...
;         float ss = 0.f;
; #pragma unroll
;         for (int j = 0; j < 8; ++j) ss += (y[j].x * y[j].x + y[j].y * y[j].y) + (y[j].z * y[j].z + y[j].w * y[j].w);
;         const float r = rsqrtf(wave_sum(ss) * (1.f / DM) + EPS);
;         f32x4* xo = (f32x4*)(Xd + (size_t)row * DM) + lane; float s2 = 0.f;
; #pragma unroll
;         for (int j = 0; j < 8; ++j) { const f32x4 gg = ((const f32x4*)gpost)[lane + 64 * j]; x[j] = x[j] + y[j] * r * gg; __builtin_nontemporal_store(x[j], xo + 64 * j);
;             s2 += (x[j].x * x[j].x + x[j].y * x[j].y) + (x[j].z * x[j].z + x[j].w * x[j].w); }
.LBB0_483:
	v_mov_b32_e32 v170, v121
	v_mov_b32_e32 v171, v125
	v_mov_b32_e32 v158, v120
	v_mov_b32_e32 v159, v124
	v_pk_mul_f32 v[170:171], v[170:171], v[170:171]
	v_mov_b32_e32 v172, v123
	v_mov_b32_e32 v173, v127
	v_pk_fma_f32 v[158:159], v[158:159], v[158:159], v[170:171]
	v_mov_b32_e32 v170, v122
	v_mov_b32_e32 v171, v126
	v_pk_mul_f32 v[172:173], v[172:173], v[172:173]
	s_mov_b32 s9, -1
	v_pk_fma_f32 v[170:171], v[170:171], v[170:171], v[172:173]
	v_pk_mul_f32 v[172:173], v[116:117], v[116:117]
	v_pk_add_f32 v[158:159], v[158:159], v[170:171]
	v_pk_mul_f32 v[170:171], v[118:119], v[118:119]
	v_pk_add_f32 v[158:159], v[158:159], v[158:159] op_sel_hi:[0,1]
	v_pk_mov_b32 v[174:175], v[172:173], v[170:171] op_sel:[1,0]
	v_mov_b32_e32 v173, v171
	v_mul_f32_e32 v158, v112, v112
	v_pk_add_f32 v[170:171], v[174:175], v[172:173]
	v_pk_fma_f32 v[172:173], v[112:113], v[112:113], v[158:159] op_sel_hi:[1,1,0]
	v_mul_f32_e32 v158, v114, v114
	v_pk_add_f32 v[170:171], v[170:171], v[170:171] op_sel_hi:[0,1]
	v_pk_fma_f32 v[174:175], v[114:115], v[114:115], v[158:159] op_sel_hi:[1,1,0]
	v_mul_f32_e32 v172, v108, v108
	v_mul_f32_e32 v174, v109, v109
	v_mul_f32_e32 v170, v110, v110
	v_mul_f32_e32 v158, v111, v111
	v_pk_add_f32 v[172:173], v[172:173], v[174:175]
	v_pk_add_f32 v[158:159], v[170:171], v[158:159]
	v_pk_mul_f32 v[170:171], v[106:107], v[106:107]
	v_pk_add_f32 v[158:159], v[172:173], v[158:159]
	v_pk_mul_f32 v[172:173], v[104:105], v[104:105]
	v_pk_add_f32 v[158:159], v[158:159], v[158:159] op_sel_hi:[0,1]
	v_pk_mov_b32 v[174:175], v[172:173], v[170:171] op_sel:[1,0]
	v_mov_b32_e32 v173, v171
	v_mul_f32_e32 v158, v100, v100
	v_pk_add_f32 v[170:171], v[174:175], v[172:173]
	v_pk_fma_f32 v[172:173], v[100:101], v[100:101], v[158:159] op_sel_hi:[1,1,0]
	v_mul_f32_e32 v158, v102, v102
	v_pk_add_f32 v[170:171], v[170:171], v[170:171] op_sel_hi:[0,1]
	v_pk_fma_f32 v[174:175], v[102:103], v[102:103], v[158:159] op_sel_hi:[1,1,0]
	v_mul_f32_e32 v172, v96, v96
	v_mul_f32_e32 v174, v97, v97
	v_mul_f32_e32 v170, v98, v98
	v_mul_f32_e32 v158, v99, v99
	v_pk_add_f32 v[172:173], v[172:173], v[174:175]
	v_pk_add_f32 v[158:159], v[170:171], v[158:159]
	s_mov_b64 s[16:17], -1
	v_pk_add_f32 v[158:159], v[172:173], v[158:159]
	s_nop 0
	v_add_f32_e32 v129, v158, v159
	v_mbcnt_lo_u32_b32 v158, s9, 0
	v_mbcnt_hi_u32_b32 v158, s9, v158
	v_lshlrev_b32_e32 v158, 2, v158
	v_xor_b32_e32 v158, 4, v158
	ds_bpermute_b32 v158, v158, v129
	s_mov_b32 s9, -1
	s_waitcnt lgkmcnt(0)
	v_add_f32_e32 v129, v129, v158
	v_mbcnt_lo_u32_b32 v158, s9, 0
	v_mbcnt_hi_u32_b32 v158, s9, v158
	v_lshlrev_b32_e32 v158, 2, v158
	v_xor_b32_e32 v158, 8, v158
	ds_bpermute_b32 v158, v158, v129
	s_mov_b32 s9, -1
	s_waitcnt lgkmcnt(0)
	v_add_f32_e32 v129, v129, v158
	v_mbcnt_lo_u32_b32 v158, s9, 0
	v_mbcnt_hi_u32_b32 v158, s9, v158
	v_lshlrev_b32_e32 v158, 2, v158
	v_xor_b32_e32 v158, 16, v158
	ds_bpermute_b32 v158, v158, v129
	s_mov_b32 s9, -1
	s_waitcnt lgkmcnt(0)
	v_add_f32_e32 v129, v129, v158
	v_mbcnt_lo_u32_b32 v158, s9, 0
	v_mbcnt_hi_u32_b32 v158, s9, v158
	v_lshlrev_b32_e32 v158, 2, v158
	v_xor_b32_e32 v158, 32, v158
	ds_bpermute_b32 v158, v158, v129
	s_mov_b32 s9, -1
	s_waitcnt lgkmcnt(0)
	v_add_f32_e32 v129, v129, v158
	v_mbcnt_lo_u32_b32 v158, s9, 0
	v_mbcnt_hi_u32_b32 v158, s9, v158
	s_mov_b32 s9, -1
	v_lshlrev_b32_e32 v158, 2, v158
	v_xor_b32_e32 v158, 64, v158
	ds_bpermute_b32 v158, v158, v129
	s_waitcnt lgkmcnt(0)
	v_add_f32_e32 v129, v129, v158
	v_mbcnt_lo_u32_b32 v158, s9, 0
	v_mbcnt_hi_u32_b32 v158, s9, v158
	v_lshlrev_b32_e32 v158, 2, v158
	v_xor_b32_e32 v158, 0x80, v158
	ds_bpermute_b32 v158, v158, v129
	s_mov_b32 s9, -1
	s_waitcnt lgkmcnt(0)
	v_add_f32_e32 v129, v129, v158
	v_fmamk_f32 v129, v129, 0x3a000000, v203
	v_cmp_gt_f32_e32 vcc, s2, v129
	v_mul_f32_e32 v158, 0x4b800000, v129
	s_nop 0
	v_cndmask_b32_e32 v129, v129, v158, vcc
	v_rsq_f32_e32 v129, v129
	s_nop 0
	v_mul_f32_e32 v158, 0x45800000, v129
	v_cndmask_b32_e32 v158, v129, v158, vcc
	v_pk_mul_f32 v[124:125], v[124:125], v[158:159] op_sel_hi:[1,0]
	v_pk_mul_f32 v[126:127], v[126:127], v[158:159] op_sel_hi:[1,0]
	v_pk_mul_f32 v[122:123], v[122:123], v[158:159] op_sel_hi:[1,0]
	v_pk_mul_f32 v[120:121], v[120:121], v[158:159] op_sel_hi:[1,0]
	v_pk_mul_f32 v[118:119], v[118:119], v[158:159] op_sel_hi:[1,0]
	v_pk_mul_f32 v[116:117], v[116:117], v[158:159] op_sel_hi:[1,0]
	v_pk_mul_f32 v[114:115], v[114:115], v[158:159] op_sel_hi:[1,0]
	v_pk_mul_f32 v[112:113], v[112:113], v[158:159] op_sel_hi:[1,0]
	v_pk_mul_f32 v[108:109], v[108:109], v[158:159] op_sel_hi:[1,0]
	v_pk_mul_f32 v[110:111], v[110:111], v[158:159] op_sel_hi:[1,0]
	v_pk_mul_f32 v[106:107], v[106:107], v[158:159] op_sel_hi:[1,0]
	v_pk_mul_f32 v[104:105], v[104:105], v[158:159] op_sel_hi:[1,0]
	v_pk_mul_f32 v[102:103], v[102:103], v[158:159] op_sel_hi:[1,0]
	v_pk_mul_f32 v[100:101], v[100:101], v[158:159] op_sel_hi:[1,0]
	v_pk_mul_f32 v[98:99], v[98:99], v[158:159] op_sel_hi:[1,0]
	v_pk_mul_f32 v[96:97], v[96:97], v[158:159] op_sel_hi:[1,0]
	v_pk_fma_f32 v[94:95], v[182:183], v[126:127], v[94:95]
	v_pk_fma_f32 v[92:93], v[180:181], v[124:125], v[92:93]
	global_store_dwordx4 v[154:155], v[92:95], off offset:-4096 nt
	v_pk_fma_f32 v[88:89], v[184:185], v[120:121], v[88:89]
	v_pk_fma_f32 v[90:91], v[186:187], v[122:123], v[90:91]
	global_store_dwordx4 v[154:155], v[88:91], off offset:-3072 nt
	v_pk_fma_f32 v[84:85], v[188:189], v[116:117], v[84:85]
	v_pk_fma_f32 v[86:87], v[190:191], v[118:119], v[86:87]
	global_store_dwordx4 v[154:155], v[84:87], off offset:-2048 nt
	v_pk_fma_f32 v[80:81], v[192:193], v[112:113], v[80:81]
	v_pk_fma_f32 v[82:83], v[194:195], v[114:115], v[82:83]
; DI unsigned pk2(float lo, float hi) { f32x2_t v = {lo, hi}; bf16x2_t b = __builtin_convertvector(v, bf16x2_t); return __builtin_bit_cast(unsigned, b); }
; DI void resnorm_rows(const float* Y, const float* Xs, float* Xd, const float* gpost, const float* gpre, bf16* H, int gw, int NGW, int lane) {
;     ...
;         for (int j = 0; j < 8; ++j) { const f32x4 gg = ((const f32x4*)gpost)[lane + 64 * j]; x[j] = x[j] + y[j] * r * gg; __builtin_nontemporal_store(x[j], xo + 64 * j);
;             s2 += (x[j].x * x[j].x + x[j].y * x[j].y) + (x[j].z * x[j].z + x[j].w * x[j].w); }
;         if (H) {
;             const float r2 = rsqrtf(wave_sum(s2) * (1.f / DM) + EPS);
;             u32x2* o = (u32x2*)(H + (size_t)row * DM) + lane;
; #pragma unroll
;             for (int j = 0; j < 8; ++j) { const f32x4 gg = ((const f32x4*)gpre)[lane + 64 * j]; u32x2 w; w.x = pk2(x[j].x * r2 * gg.x, x[j].y * r2 * gg.y); w.y = pk2(x[j].z * r2 * gg.z, x[j].w * r2 * gg.w); o[64 * j] = w; }
	global_store_dwordx4 v[154:155], v[80:83], off offset:-1024 nt
	v_pk_fma_f32 v[78:79], v[198:199], v[110:111], v[78:79]
	v_pk_fma_f32 v[76:77], v[196:197], v[108:109], v[76:77]
	global_store_dwordx4 v[154:155], v[76:79], off nt
	v_pk_fma_f32 v[72:73], v[208:209], v[104:105], v[72:73]
	v_pk_fma_f32 v[74:75], v[210:211], v[106:107], v[74:75]
	global_store_dwordx4 v[154:155], v[72:75], off offset:1024 nt
	v_pk_fma_f32 v[68:69], v[100:101], v[212:213], v[68:69]
	v_pk_fma_f32 v[70:71], v[102:103], v[214:215], v[70:71]
	global_store_dwordx4 v[154:155], v[68:71], off offset:2048 nt
	v_pk_fma_f32 v[66:67], v[98:99], v[218:219], v[66:67]
	v_mov_b32_e32 v98, v93
	v_mov_b32_e32 v99, v89
	v_pk_fma_f32 v[64:65], v[96:97], v[216:217], v[64:65]
	v_mov_b32_e32 v96, v92
	v_mov_b32_e32 v97, v88
	v_pk_mul_f32 v[98:99], v[98:99], v[98:99]
	v_mov_b32_e32 v100, v95
	v_mov_b32_e32 v101, v91
	v_pk_fma_f32 v[96:97], v[96:97], v[96:97], v[98:99]
	v_mov_b32_e32 v98, v94
	v_mov_b32_e32 v99, v90
	v_pk_mul_f32 v[100:101], v[100:101], v[100:101]
	global_store_dwordx4 v[154:155], v[64:67], off offset:3072 nt
	v_pk_fma_f32 v[98:99], v[98:99], v[98:99], v[100:101]
	v_pk_mul_f32 v[100:101], v[86:87], v[86:87]
	v_pk_add_f32 v[96:97], v[96:97], v[98:99]
	v_pk_mul_f32 v[98:99], v[84:85], v[84:85]
	v_pk_add_f32 v[96:97], v[96:97], v[96:97] op_sel_hi:[0,1]
	v_pk_mov_b32 v[102:103], v[98:99], v[100:101] op_sel:[1,0]
	v_mov_b32_e32 v99, v101
	v_mul_f32_e32 v96, v80, v80
	v_pk_add_f32 v[98:99], v[102:103], v[98:99]
	v_pk_fma_f32 v[100:101], v[80:81], v[80:81], v[96:97] op_sel_hi:[1,1,0]
	v_mul_f32_e32 v96, v82, v82
	v_pk_add_f32 v[98:99], v[98:99], v[98:99] op_sel_hi:[0,1]
	v_pk_fma_f32 v[102:103], v[82:83], v[82:83], v[96:97] op_sel_hi:[1,1,0]
	v_mul_f32_e32 v100, v76, v76
	v_mul_f32_e32 v102, v77, v77
	v_mul_f32_e32 v98, v78, v78
	v_mul_f32_e32 v96, v79, v79
	v_pk_add_f32 v[100:101], v[100:101], v[102:103]
	v_pk_add_f32 v[96:97], v[98:99], v[96:97]
	v_pk_mul_f32 v[98:99], v[72:73], v[72:73]
	v_pk_add_f32 v[96:97], v[100:101], v[96:97]
	v_pk_mul_f32 v[100:101], v[74:75], v[74:75]
	v_pk_add_f32 v[96:97], v[96:97], v[96:97] op_sel_hi:[0,1]
	v_pk_mov_b32 v[102:103], v[98:99], v[100:101] op_sel:[1,0]
	v_mov_b32_e32 v99, v101
	v_mul_f32_e32 v96, v68, v68
	v_pk_add_f32 v[98:99], v[102:103], v[98:99]
	v_pk_fma_f32 v[100:101], v[68:69], v[68:69], v[96:97] op_sel_hi:[1,1,0]
	v_mul_f32_e32 v96, v70, v70
	v_pk_add_f32 v[98:99], v[98:99], v[98:99] op_sel_hi:[0,1]
	v_pk_fma_f32 v[102:103], v[70:71], v[70:71], v[96:97] op_sel_hi:[1,1,0]
	v_mul_f32_e32 v100, v64, v64
	v_mul_f32_e32 v102, v65, v65
	v_mul_f32_e32 v98, v66, v66
	v_mul_f32_e32 v96, v67, v67
	v_pk_add_f32 v[100:101], v[100:101], v[102:103]
	v_pk_add_f32 v[96:97], v[98:99], v[96:97]
	s_nop 0
	v_pk_add_f32 v[96:97], v[100:101], v[96:97]
	s_nop 0
	v_add_f32_e32 v96, v96, v97
	v_mbcnt_lo_u32_b32 v97, s9, 0
	v_mbcnt_hi_u32_b32 v97, s9, v97
	v_lshlrev_b32_e32 v97, 2, v97
	v_xor_b32_e32 v97, 4, v97
	ds_bpermute_b32 v97, v97, v96
	s_mov_b32 s9, -1
	s_waitcnt lgkmcnt(0)
	v_add_f32_e32 v96, v96, v97
	v_mbcnt_lo_u32_b32 v97, s9, 0
	v_mbcnt_hi_u32_b32 v97, s9, v97
	v_lshlrev_b32_e32 v97, 2, v97
	v_xor_b32_e32 v97, 8, v97
	ds_bpermute_b32 v97, v97, v96
	s_mov_b32 s9, -1
	s_waitcnt lgkmcnt(0)
	v_add_f32_e32 v96, v96, v97
	v_mbcnt_lo_u32_b32 v97, s9, 0
	v_mbcnt_hi_u32_b32 v97, s9, v97
	v_lshlrev_b32_e32 v97, 2, v97
	v_xor_b32_e32 v97, 16, v97
	ds_bpermute_b32 v97, v97, v96
	s_mov_b32 s9, -1
	s_waitcnt lgkmcnt(0)
	v_add_f32_e32 v96, v96, v97
	v_mbcnt_lo_u32_b32 v97, s9, 0
	v_mbcnt_hi_u32_b32 v97, s9, v97
	v_lshlrev_b32_e32 v97, 2, v97
	v_xor_b32_e32 v97, 32, v97
	ds_bpermute_b32 v97, v97, v96
	s_mov_b32 s9, -1
	s_waitcnt lgkmcnt(0)
	v_add_f32_e32 v96, v96, v97
	v_mbcnt_lo_u32_b32 v97, s9, 0
	v_mbcnt_hi_u32_b32 v97, s9, v97
	v_lshlrev_b32_e32 v97, 2, v97
	v_xor_b32_e32 v97, 64, v97
	ds_bpermute_b32 v97, v97, v96
	s_mov_b32 s9, -1
	s_waitcnt lgkmcnt(0)
	v_add_f32_e32 v96, v96, v97
	v_mbcnt_lo_u32_b32 v97, s9, 0
	v_mbcnt_hi_u32_b32 v97, s9, v97
	v_lshlrev_b32_e32 v97, 2, v97
	v_xor_b32_e32 v97, 0x80, v97
	ds_bpermute_b32 v97, v97, v96
	s_waitcnt lgkmcnt(0)
	v_add_f32_e32 v96, v96, v97
	v_fmamk_f32 v96, v96, 0x3a000000, v203
	v_cmp_gt_f32_e32 vcc, s2, v96
	v_mul_f32_e32 v97, 0x4b800000, v96
	s_nop 0
	v_cndmask_b32_e32 v96, v96, v97, vcc
	v_rsq_f32_e32 v96, v96
	s_nop 0
	v_mul_f32_e32 v97, 0x45800000, v96
	v_cndmask_b32_e32 v100, v96, v97, vcc
	v_pk_mul_f32 v[92:93], v[92:93], v[100:101] op_sel_hi:[1,0]
	v_pk_mul_f32 v[94:95], v[94:95], v[100:101] op_sel_hi:[1,0]
	v_pk_mul_f32 v[88:89], v[88:89], v[100:101] op_sel_hi:[1,0]
	v_pk_mul_f32 v[90:91], v[90:91], v[100:101] op_sel_hi:[1,0]
	v_pk_mul_f32 v[84:85], v[84:85], v[100:101] op_sel_hi:[1,0]
	v_pk_mul_f32 v[86:87], v[86:87], v[100:101] op_sel_hi:[1,0]
	v_pk_mul_f32 v[80:81], v[80:81], v[100:101] op_sel_hi:[1,0]
	v_pk_mul_f32 v[82:83], v[82:83], v[100:101] op_sel_hi:[1,0]
	v_pk_mul_f32 v[76:77], v[76:77], v[100:101] op_sel_hi:[1,0]
	v_pk_mul_f32 v[78:79], v[78:79], v[100:101] op_sel_hi:[1,0]
	v_pk_mul_f32 v[72:73], v[72:73], v[100:101] op_sel_hi:[1,0]
	v_pk_mul_f32 v[74:75], v[74:75], v[100:101] op_sel_hi:[1,0]
	v_pk_mul_f32 v[68:69], v[68:69], v[100:101] op_sel_hi:[1,0]
	v_pk_mul_f32 v[70:71], v[70:71], v[100:101] op_sel_hi:[1,0]
	v_pk_mul_f32 v[64:65], v[64:65], v[100:101] op_sel_hi:[1,0]
	v_pk_mul_f32 v[66:67], v[66:67], v[100:101] op_sel_hi:[1,0]
	s_andn2_b64 vcc, exec, s[14:15]
	v_pk_mul_f32 v[92:93], v[220:221], v[92:93]
	v_pk_mul_f32 v[94:95], v[222:223], v[94:95]
	v_cvt_pk_bf16_f32 v92, v92, v93
	v_cvt_pk_bf16_f32 v93, v94, v95
	global_store_dwordx2 v[156:157], v[92:93], off offset:-2048
; DI unsigned pk2(float lo, float hi) { f32x2_t v = {lo, hi}; bf16x2_t b = __builtin_convertvector(v, bf16x2_t); return __builtin_bit_cast(unsigned, b); }
; DI void norm_rows(const float* src, int nrows, const float* g, bf16* dst, int gw, int NGW, int lane) {
;     int row = gw; if (row >= nrows) return;
;     f32x4 v[8], vn[8];
;     { const f32x4* xr = (const f32x4*)(src + (size_t)row * DM) + lane;
; #pragma unroll
;       for (int j = 0; j < 8; ++j) v[j] = __builtin_nontemporal_load(xr + 64 * j); }
; DI void resnorm_rows(const float* Y, const float* Xs, float* Xd, const float* gpost, const float* gpre, bf16* H, int gw, int NGW, int lane) {
;     ...
;             for (int j = 0; j < 8; ++j) { const f32x4 gg = ((const f32x4*)gpre)[lane + 64 * j]; u32x2 w; w.x = pk2(x[j].x * r2 * gg.x, x[j].y * r2 * gg.y); w.y = pk2(x[j].z * r2 * gg.z, x[j].w * r2 * gg.w); o[64 * j] = w; }
;         }
;         if (!has) break;
; #pragma unroll
;         for (int j = 0; j < 8; ++j) { y[j] = yn[j]; x[j] = xn[j]; }
;         row = nrow;
	v_pk_mul_f32 v[88:89], v[224:225], v[88:89]
	v_pk_mul_f32 v[90:91], v[226:227], v[90:91]
	v_cvt_pk_bf16_f32 v88, v88, v89
	v_cvt_pk_bf16_f32 v89, v90, v91
	global_store_dwordx2 v[156:157], v[88:89], off offset:-1536
	v_pk_mul_f32 v[84:85], v[228:229], v[84:85]
	v_pk_mul_f32 v[86:87], v[230:231], v[86:87]
	v_cvt_pk_bf16_f32 v84, v84, v85
	v_cvt_pk_bf16_f32 v85, v86, v87
	global_store_dwordx2 v[156:157], v[84:85], off offset:-1024
	v_pk_mul_f32 v[80:81], v[232:233], v[80:81]
	v_pk_mul_f32 v[82:83], v[234:235], v[82:83]
	v_cvt_pk_bf16_f32 v80, v80, v81
	v_cvt_pk_bf16_f32 v81, v82, v83
	global_store_dwordx2 v[156:157], v[80:81], off offset:-512
	v_pk_mul_f32 v[76:77], v[76:77], v[236:237]
	v_pk_mul_f32 v[78:79], v[78:79], v[238:239]
	v_cvt_pk_bf16_f32 v76, v76, v77
	v_cvt_pk_bf16_f32 v77, v78, v79
	global_store_dwordx2 v[156:157], v[76:77], off
	v_pk_mul_f32 v[72:73], v[72:73], v[240:241]
	v_pk_mul_f32 v[74:75], v[74:75], v[242:243]
	v_cvt_pk_bf16_f32 v72, v72, v73
	v_cvt_pk_bf16_f32 v73, v74, v75
	global_store_dwordx2 v[156:157], v[72:73], off offset:512
	v_pk_mul_f32 v[68:69], v[68:69], v[244:245]
	v_pk_mul_f32 v[70:71], v[70:71], v[246:247]
	v_cvt_pk_bf16_f32 v68, v68, v69
	v_cvt_pk_bf16_f32 v69, v70, v71
	global_store_dwordx2 v[156:157], v[68:69], off offset:1024
	v_pk_mul_f32 v[64:65], v[64:65], v[248:249]
	v_pk_mul_f32 v[66:67], v[66:67], v[250:251]
	v_cvt_pk_bf16_f32 v64, v64, v65
	v_cvt_pk_bf16_f32 v65, v66, v67
	global_store_dwordx2 v[156:157], v[64:65], off offset:1536
	s_cbranch_vccnz .LBB0_480
	s_waitcnt vmcnt(16)
	v_readlane_b32 s14, v254, 50
	v_readlane_b32 s15, v254, 51
	s_add_i32 s12, s12, s62
	s_mov_b64 s[16:17], 0
	v_lshl_add_u64 v[154:155], v[154:155], 0, s[14:15]
	v_readlane_b32 s14, v254, 54
	v_readlane_b32 s15, v254, 55
	v_mov_b32_e32 v67, v59
	v_mov_b32_e32 v66, v58
	v_lshl_add_u64 v[156:157], v[156:157], 0, s[14:15]
	v_mov_b32_e32 v65, v57
	v_mov_b32_e32 v64, v56
	v_mov_b32_e32 v71, v63
	v_mov_b32_e32 v70, v62
	v_mov_b32_e32 v69, v61
	v_mov_b32_e32 v68, v60
	v_mov_b32_e32 v75, v51
	v_mov_b32_e32 v74, v50
	v_mov_b32_e32 v73, v49
	v_mov_b32_e32 v72, v48
	v_mov_b32_e32 v79, v55
	v_mov_b32_e32 v78, v54
	v_mov_b32_e32 v77, v53
	v_mov_b32_e32 v76, v52
	v_mov_b32_e32 v83, v27
	v_mov_b32_e32 v82, v26
	v_mov_b32_e32 v81, v25
	v_mov_b32_e32 v80, v24
	v_mov_b32_e32 v87, v31
	v_mov_b32_e32 v86, v30
	v_mov_b32_e32 v85, v29
	v_mov_b32_e32 v84, v28
	v_mov_b32_e32 v91, v19
	v_mov_b32_e32 v90, v18
	v_mov_b32_e32 v89, v17
	v_mov_b32_e32 v88, v16
	v_mov_b32_e32 v95, v23
	v_mov_b32_e32 v94, v22
	v_mov_b32_e32 v93, v21
	v_mov_b32_e32 v92, v20
	s_branch .LBB0_480
.LBB0_485:
	s_cmpk_gt_i32 s8, 0x3ff
	s_cbranch_scc1 .LBB0_492
	v_readlane_b32 s40, v252, 20
	v_readlane_b32 s41, v252, 21
	v_readlane_b32 s42, v252, 22
	v_readlane_b32 s43, v252, 23
	v_readlane_b32 s44, v252, 24
	v_readlane_b32 s45, v252, 25
	v_readlane_b32 s46, v252, 26
	v_readlane_b32 s47, v252, 27
	v_readlane_b32 s48, v252, 28
	v_readlane_b32 s49, v252, 29
	v_readlane_b32 s50, v252, 30
	v_readlane_b32 s51, v252, 31
	v_readlane_b32 s52, v252, 32
	v_readlane_b32 s53, v252, 33
	v_readlane_b32 s54, v252, 34
	v_readlane_b32 s55, v252, 35
	s_mov_b64 s[40:41], s[44:45]
	s_lshl_b64 s[12:13], s[10:11], 2
	s_mov_b64 s[42:43], s[46:47]
	s_mov_b64 s[44:45], s[48:49]
	s_mov_b64 s[46:47], s[50:51]
	s_mov_b64 s[48:49], s[52:53]
	s_mov_b64 s[50:51], s[54:55]
	s_add_u32 s12, s46, s12
	s_addc_u32 s13, s47, s13
	s_ashr_i32 s9, s8, 31
	v_readlane_b32 s40, v252, 4
	s_lshl_b64 s[8:9], s[8:9], 13
	v_readlane_b32 s42, v252, 6
	v_readlane_b32 s43, v252, 7
	s_add_u32 s8, s42, s8
	s_addc_u32 s9, s43, s9
	v_lshl_add_u64 v[0:1], s[8:9], 0, v[160:161]
	global_load_dwordx4 v[60:63], v160, s[8:9] nt
	global_load_dwordx4 v[56:59], v160, s[8:9] offset:1024 nt
	global_load_dwordx4 v[52:55], v160, s[8:9] offset:2048 nt
	global_load_dwordx4 v[48:51], v160, s[8:9] offset:3072 nt
	s_movk_i32 s8, 0x1000
	v_add_co_u32_e32 v0, vcc, s8, v0
	v_lshl_add_u64 v[66:67], s[12:13], 0, v[160:161]
	s_nop 0
	v_addc_co_u32_e32 v1, vcc, 0, v1, vcc
	global_load_dwordx4 v[44:47], v[0:1], off nt
	global_load_dwordx4 v[40:43], v[0:1], off offset:1024 nt
	global_load_dwordx4 v[36:39], v[0:1], off offset:2048 nt
	global_load_dwordx4 v[32:35], v[0:1], off offset:3072 nt
	s_mov_b64 s[8:9], 0x1400
	v_lshl_add_u64 v[70:71], v[66:67], 0, s[8:9]
	s_mov_b64 s[8:9], 0x1800
	v_lshl_add_u64 v[72:73], v[66:67], 0, s[8:9]
	s_mov_b64 s[8:9], 0x1c00
	v_lshl_add_u64 v[74:75], v[66:67], 0, s[8:9]
	v_readlane_b32 s8, v254, 49
	s_add_i32 s8, s8, s18
	s_ashr_i32 s9, s18, 31
	v_readlane_b32 s12, v252, 36
	s_add_u32 s12, s12, s18
	v_readlane_b32 s13, v254, 48
	s_addc_u32 s13, s13, s9
	s_lshl_b64 s[12:13], s[12:13], 12
	s_add_u32 s0, s0, s12
	s_addc_u32 s1, s1, s13
	v_readlane_b32 s9, v254, 56
	s_add_u32 s0, s9, s0
	v_readlane_b32 s9, v254, 57
	v_mov_b32_e32 v129, v161
	s_addc_u32 s1, s9, s1
	v_lshl_add_u64 v[64:65], s[42:43], 0, v[160:161]
	v_lshl_add_u64 v[68:69], v[66:67], 0, s[76:77]
	v_lshl_add_u64 v[76:77], s[0:1], 0, v[128:129]
	v_readlane_b32 s41, v252, 5
	v_readlane_b32 s44, v252, 8
	v_readlane_b32 s45, v252, 9
	v_readlane_b32 s46, v252, 10
	v_readlane_b32 s47, v252, 11
	v_readlane_b32 s48, v252, 12
	v_readlane_b32 s49, v252, 13
	v_readlane_b32 s50, v252, 14
	v_readlane_b32 s51, v252, 15
	v_readlane_b32 s52, v252, 16
	v_readlane_b32 s53, v252, 17
	v_readlane_b32 s54, v252, 18
	v_readlane_b32 s55, v252, 19
	global_load_dwordx4 v[180:183], v[66:67], off
	global_load_dwordx4 v[184:187], v[66:67], off offset:1024
	global_load_dwordx4 v[188:191], v[66:67], off offset:2048
	global_load_dwordx4 v[192:195], v[66:67], off offset:3072
	global_load_dwordx4 v[196:199], v[68:69], off
	global_load_dwordx4 v[208:211], v[70:71], off
	global_load_dwordx4 v[212:215], v[72:73], off
	global_load_dwordx4 v[216:219], v[74:75], off
	s_waitcnt vmcnt(0)
	s_branch .LBB0_488

; DI unsigned pk2(float lo, float hi) { f32x2_t v = {lo, hi}; bf16x2_t b = __builtin_convertvector(v, bf16x2_t); return __builtin_bit_cast(unsigned, b); }
; DI void norm_rows(const float* src, int nrows, const float* g, bf16* dst, int gw, int NGW, int lane) {
;     ...
;         float ss = 0.f;
; #pragma unroll
;         for (int j = 0; j < 8; ++j) ss += (v[j].x * v[j].x + v[j].y * v[j].y) + (v[j].z * v[j].z + v[j].w * v[j].w);
;         const float r = rsqrtf(wave_sum(ss) * (1.f / DM) + EPS);
;         u32x2* o = (u32x2*)(dst + (size_t)row * DM) + lane;
; #pragma unroll
;         for (int j = 0; j < 8; ++j) { const f32x4 gg = ((const f32x4*)g)[lane + 64 * j]; u32x2 w; w.x = pk2(v[j].x * r * gg.x, v[j].y * r * gg.y); w.y = pk2(v[j].z * r * gg.z, v[j].w * r * gg.w); o[64 * j] = w; }
.LBB0_490:
	v_pk_mul_f32 v[90:91], v[60:61], v[60:61]
	v_pk_mul_f32 v[92:93], v[56:57], v[56:57]
	v_pk_mul_f32 v[86:87], v[62:63], v[62:63]
	v_pk_mul_f32 v[88:89], v[58:59], v[58:59]
	v_mov_b32_e32 v94, v90
	v_mov_b32_e32 v95, v92
	v_mov_b32_e32 v92, v91
	v_pk_mul_f32 v[82:83], v[54:55], v[54:55]
	v_pk_mul_f32 v[84:85], v[52:53], v[52:53]
	v_pk_add_f32 v[90:91], v[94:95], v[92:93]
	v_mov_b32_e32 v92, v86
	v_mov_b32_e32 v93, v88
	v_mov_b32_e32 v88, v87
	v_pk_add_f32 v[86:87], v[92:93], v[88:89]
	v_pk_mov_b32 v[88:89], v[84:85], v[82:83] op_sel:[1,0]
	v_mov_b32_e32 v85, v83
	v_pk_add_f32 v[82:83], v[88:89], v[84:85]
	v_pk_add_f32 v[86:87], v[90:91], v[86:87]
	v_pk_add_f32 v[82:83], v[82:83], v[82:83] op_sel_hi:[0,1]
	v_mul_f32_e32 v82, v48, v48
	v_pk_fma_f32 v[84:85], v[48:49], v[48:49], v[82:83] op_sel_hi:[1,1,0]
	v_mul_f32_e32 v82, v50, v50
	v_pk_add_f32 v[86:87], v[86:87], v[86:87] op_sel_hi:[0,1]
	v_pk_fma_f32 v[88:89], v[50:51], v[50:51], v[82:83] op_sel_hi:[1,1,0]
	v_mul_f32_e32 v84, v44, v44
	v_mul_f32_e32 v88, v45, v45
	v_mul_f32_e32 v82, v46, v46
	v_mul_f32_e32 v86, v47, v47
	v_pk_mul_f32 v[78:79], v[42:43], v[42:43]
	v_pk_mul_f32 v[80:81], v[40:41], v[40:41]
	v_pk_add_f32 v[84:85], v[84:85], v[88:89]
	v_pk_add_f32 v[82:83], v[82:83], v[86:87]
	s_mov_b32 s9, -1
	v_pk_add_f32 v[82:83], v[84:85], v[82:83]
	v_pk_mov_b32 v[84:85], v[80:81], v[78:79] op_sel:[1,0]
	v_mov_b32_e32 v81, v79
	v_pk_add_f32 v[78:79], v[84:85], v[80:81]
	v_pk_add_f32 v[82:83], v[82:83], v[82:83] op_sel_hi:[0,1]
	v_pk_add_f32 v[78:79], v[78:79], v[78:79] op_sel_hi:[0,1]
	v_mul_f32_e32 v78, v36, v36
	v_pk_fma_f32 v[80:81], v[36:37], v[36:37], v[78:79] op_sel_hi:[1,1,0]
	v_mul_f32_e32 v78, v38, v38
	v_pk_fma_f32 v[84:85], v[38:39], v[38:39], v[78:79] op_sel_hi:[1,1,0]
	v_mul_f32_e32 v80, v32, v32
	v_mul_f32_e32 v84, v33, v33
	v_mul_f32_e32 v78, v34, v34
	v_mul_f32_e32 v82, v35, v35
	v_pk_add_f32 v[80:81], v[80:81], v[84:85]
	v_pk_add_f32 v[78:79], v[78:79], v[82:83]
	s_mov_b64 s[12:13], -1
	v_pk_add_f32 v[78:79], v[80:81], v[78:79]
	s_nop 0
	v_add_f32_e32 v78, v78, v79
	v_mbcnt_lo_u32_b32 v79, s9, 0
	v_mbcnt_hi_u32_b32 v79, s9, v79
	v_lshlrev_b32_e32 v79, 2, v79
	v_xor_b32_e32 v79, 4, v79
	ds_bpermute_b32 v79, v79, v78
	s_mov_b32 s9, -1
	s_waitcnt lgkmcnt(0)
	v_add_f32_e32 v78, v78, v79
	v_mbcnt_lo_u32_b32 v79, s9, 0
	v_mbcnt_hi_u32_b32 v79, s9, v79
	v_lshlrev_b32_e32 v79, 2, v79
	v_xor_b32_e32 v79, 8, v79
	ds_bpermute_b32 v79, v79, v78
	s_mov_b32 s9, -1
	s_waitcnt lgkmcnt(0)
	v_add_f32_e32 v78, v78, v79
	v_mbcnt_lo_u32_b32 v79, s9, 0
	v_mbcnt_hi_u32_b32 v79, s9, v79
	v_lshlrev_b32_e32 v79, 2, v79
	v_xor_b32_e32 v79, 16, v79
	ds_bpermute_b32 v79, v79, v78
	s_mov_b32 s9, -1
	s_waitcnt lgkmcnt(0)
	v_add_f32_e32 v78, v78, v79
	v_mbcnt_lo_u32_b32 v79, s9, 0
	v_mbcnt_hi_u32_b32 v79, s9, v79
	v_lshlrev_b32_e32 v79, 2, v79
	v_xor_b32_e32 v79, 32, v79
	ds_bpermute_b32 v79, v79, v78
	s_mov_b32 s9, -1
	s_waitcnt lgkmcnt(0)
	v_add_f32_e32 v78, v78, v79
	v_mbcnt_lo_u32_b32 v79, s9, 0
	v_mbcnt_hi_u32_b32 v79, s9, v79
	s_mov_b32 s9, -1
	v_lshlrev_b32_e32 v79, 2, v79
	v_xor_b32_e32 v79, 64, v79
	ds_bpermute_b32 v79, v79, v78
	s_waitcnt lgkmcnt(0)
	v_add_f32_e32 v78, v78, v79
	v_mbcnt_lo_u32_b32 v79, s9, 0
	v_mbcnt_hi_u32_b32 v79, s9, v79
	v_lshlrev_b32_e32 v79, 2, v79
	v_xor_b32_e32 v79, 0x80, v79
	ds_bpermute_b32 v79, v79, v78
	s_waitcnt lgkmcnt(0)
	v_add_f32_e32 v78, v78, v79
	v_fmamk_f32 v78, v78, 0x3a000000, v203
	v_cmp_gt_f32_e32 vcc, s2, v78
	v_mul_f32_e32 v79, 0x4b800000, v78
	s_nop 0
	v_cndmask_b32_e32 v78, v78, v79, vcc
	v_rsq_f32_e32 v78, v78
	s_nop 0
	v_mul_f32_e32 v79, 0x45800000, v78
	v_cndmask_b32_e32 v78, v78, v79, vcc
	v_pk_mul_f32 v[60:61], v[60:61], v[78:79] op_sel_hi:[1,0]
	v_pk_mul_f32 v[62:63], v[62:63], v[78:79] op_sel_hi:[1,0]
	v_pk_mul_f32 v[56:57], v[56:57], v[78:79] op_sel_hi:[1,0]
	v_pk_mul_f32 v[58:59], v[58:59], v[78:79] op_sel_hi:[1,0]
	v_pk_mul_f32 v[52:53], v[52:53], v[78:79] op_sel_hi:[1,0]
	v_pk_mul_f32 v[54:55], v[54:55], v[78:79] op_sel_hi:[1,0]
	v_pk_mul_f32 v[48:49], v[48:49], v[78:79] op_sel_hi:[1,0]
	v_pk_mul_f32 v[50:51], v[50:51], v[78:79] op_sel_hi:[1,0]
	v_pk_mul_f32 v[44:45], v[44:45], v[78:79] op_sel_hi:[1,0]
	v_pk_mul_f32 v[46:47], v[46:47], v[78:79] op_sel_hi:[1,0]
	v_pk_mul_f32 v[40:41], v[40:41], v[78:79] op_sel_hi:[1,0]
	v_pk_mul_f32 v[42:43], v[42:43], v[78:79] op_sel_hi:[1,0]
	v_pk_mul_f32 v[36:37], v[36:37], v[78:79] op_sel_hi:[1,0]
	v_pk_mul_f32 v[38:39], v[38:39], v[78:79] op_sel_hi:[1,0]
	v_pk_mul_f32 v[32:33], v[32:33], v[78:79] op_sel_hi:[1,0]
	v_pk_mul_f32 v[34:35], v[34:35], v[78:79] op_sel_hi:[1,0]
	s_andn2_b64 vcc, exec, s[0:1]
	v_pk_mul_f32 v[60:61], v[180:181], v[60:61]
	v_pk_mul_f32 v[62:63], v[182:183], v[62:63]
	v_cvt_pk_bf16_f32 v60, v60, v61
	v_cvt_pk_bf16_f32 v61, v62, v63
	global_store_dwordx2 v[76:77], v[60:61], off offset:-2048
	v_pk_mul_f32 v[56:57], v[184:185], v[56:57]
	v_pk_mul_f32 v[58:59], v[186:187], v[58:59]
	v_cvt_pk_bf16_f32 v56, v56, v57
	v_cvt_pk_bf16_f32 v57, v58, v59
	global_store_dwordx2 v[76:77], v[56:57], off offset:-1536
	v_pk_mul_f32 v[52:53], v[188:189], v[52:53]
	v_pk_mul_f32 v[54:55], v[190:191], v[54:55]
	v_cvt_pk_bf16_f32 v52, v52, v53
	v_cvt_pk_bf16_f32 v53, v54, v55
	global_store_dwordx2 v[76:77], v[52:53], off offset:-1024
	v_pk_mul_f32 v[48:49], v[192:193], v[48:49]
	v_pk_mul_f32 v[50:51], v[194:195], v[50:51]
	v_cvt_pk_bf16_f32 v48, v48, v49
	v_cvt_pk_bf16_f32 v49, v50, v51
	global_store_dwordx2 v[76:77], v[48:49], off offset:-512
	v_pk_mul_f32 v[44:45], v[44:45], v[196:197]
	v_pk_mul_f32 v[46:47], v[46:47], v[198:199]
	v_cvt_pk_bf16_f32 v44, v44, v45
	v_cvt_pk_bf16_f32 v45, v46, v47
	global_store_dwordx2 v[76:77], v[44:45], off
	v_pk_mul_f32 v[40:41], v[40:41], v[208:209]
	v_pk_mul_f32 v[42:43], v[42:43], v[210:211]
	v_cvt_pk_bf16_f32 v40, v40, v41
	v_cvt_pk_bf16_f32 v41, v42, v43
	global_store_dwordx2 v[76:77], v[40:41], off offset:512
	v_pk_mul_f32 v[36:37], v[36:37], v[212:213]
	v_pk_mul_f32 v[38:39], v[38:39], v[214:215]
	v_cvt_pk_bf16_f32 v36, v36, v37
	v_cvt_pk_bf16_f32 v37, v38, v39
	global_store_dwordx2 v[76:77], v[36:37], off offset:1024
	v_pk_mul_f32 v[32:33], v[32:33], v[216:217]
	v_pk_mul_f32 v[34:35], v[34:35], v[218:219]
	v_cvt_pk_bf16_f32 v32, v32, v33
	v_cvt_pk_bf16_f32 v33, v34, v35
	global_store_dwordx2 v[76:77], v[32:33], off offset:1536
	s_cbranch_vccnz .LBB0_487
; DI void norm_rows(const float* src, int nrows, const float* g, bf16* dst, int gw, int NGW, int lane) {
;     ...
;         if (!has) break;
; #pragma unroll
;         for (int j = 0; j < 8; ++j) v[j] = vn[j];
;         row = nrow;
	s_waitcnt vmcnt(8)
	v_readlane_b32 s0, v254, 54
	v_readlane_b32 s1, v254, 55
	s_add_i32 s8, s8, s62
	s_mov_b64 s[12:13], 0
	v_lshl_add_u64 v[76:77], v[76:77], 0, s[0:1]
	v_mov_b32_e32 v35, v19
	v_mov_b32_e32 v34, v18
	v_mov_b32_e32 v33, v17
	v_mov_b32_e32 v32, v16
	v_mov_b32_e32 v39, v23
	v_mov_b32_e32 v38, v22
	v_mov_b32_e32 v37, v21
	v_mov_b32_e32 v36, v20
	v_mov_b32_e32 v43, v27
	v_mov_b32_e32 v42, v26
	v_mov_b32_e32 v41, v25
	v_mov_b32_e32 v40, v24
	v_mov_b32_e32 v47, v31
	v_mov_b32_e32 v46, v30
	v_mov_b32_e32 v45, v29
	v_mov_b32_e32 v44, v28
	v_mov_b32_e32 v51, v3
	v_mov_b32_e32 v50, v2
	v_mov_b32_e32 v49, v1
	v_mov_b32_e32 v48, v0
	v_mov_b32_e32 v55, v7
	v_mov_b32_e32 v54, v6
	v_mov_b32_e32 v53, v5
	v_mov_b32_e32 v52, v4
	v_mov_b32_e32 v59, v11
	v_mov_b32_e32 v58, v10
	v_mov_b32_e32 v57, v9
	v_mov_b32_e32 v56, v8
	v_mov_b32_e32 v63, v15
	v_mov_b32_e32 v62, v14
	v_mov_b32_e32 v61, v13
	v_mov_b32_e32 v60, v12
	s_branch .LBB0_487

; DI unsigned pk2(float lo, float hi) { f32x2_t v = {lo, hi}; bf16x2_t b = __builtin_convertvector(v, bf16x2_t); return __builtin_bit_cast(unsigned, b); }
; DI void resnorm_rows(const float* Y, const float* Xs, float* Xd, const float* gpost, const float* gpre, bf16* H, int gw, int NGW, int lane) {
;     int row = gw; if (row >= T) return;
;     f32x4 y[8], x[8], yn[8], xn[8];
;     { const f32x4* yr = (const f32x4*)(Y + (size_t)row * DM) + lane; const f32x4* xr = (const f32x4*)(Xs + (size_t)row * DM) + lane;
; #pragma unroll
;       for (int j = 0; j < 8; ++j) { y[j] = __builtin_nontemporal_load(yr + 64 * j); x[j] = __builtin_nontemporal_load(xr + 64 * j); } }
;     for (;;) {
;         const int nrow = row + NGW; const bool has = nrow < T;
;         if (has) { const f32x4* yr = (const f32x4*)(Y + (size_t)nrow * DM) + lane; const f32x4* xr = (const f32x4*)(Xs + (size_t)nrow * DM) + lane;
; #pragma unroll
;             for (int j = 0; j < 8; ++j) { yn[j] = __builtin_nontemporal_load(yr + 64 * j); xn[j] = __builtin_nontemporal_load(xr + 64 * j); } }
;     ...
;         for (int j = 0; j < 8; ++j) { const f32x4 gg = ((const f32x4*)gpost)[lane + 64 * j]; x[j] = x[j] + y[j] * r * gg; __builtin_nontemporal_store(x[j], xo + 64 * j);
;             s2 += (x[j].x * x[j].x + x[j].y * x[j].y) + (x[j].z * x[j].z + x[j].w * x[j].w); }
;         if (H) {
;             const float r2 = rsqrtf(wave_sum(s2) * (1.f / DM) + EPS);
;             u32x2* o = (u32x2*)(H + (size_t)row * DM) + lane;
; #pragma unroll
;             for (int j = 0; j < 8; ++j) { const f32x4 gg = ((const f32x4*)gpre)[lane + 64 * j]; u32x2 w; w.x = pk2(x[j].x * r2 * gg.x, x[j].y * r2 * gg.y); w.y = pk2(x[j].z * r2 * gg.z, x[j].w * r2 * gg.w); o[64 * j] = w; }
.LBB0_794:
	s_or_b64 exec, exec, s[0:1]
	s_mov_b32 s0, -1
	s_waitcnt lgkmcnt(0)
	s_barrier
	s_mov_b64 s[8:9], 0
	v_mbcnt_lo_u32_b32 v0, s0, 0
	v_mbcnt_hi_u32_b32 v0, s0, v0
	v_add_u32_e32 v0, s68, v0
	s_nop 0
	v_readfirstlane_b32 s0, v0
	s_ashr_i32 s12, s0, 6
	v_readlane_b32 s0, v252, 36
	s_add_i32 s0, s12, s0
	s_cmpk_gt_i32 s0, 0x3fff
	s_cbranch_scc1 .LBB0_801
	v_readlane_b32 s40, v252, 20
	v_readlane_b32 s41, v252, 21
	v_readlane_b32 s42, v252, 22
	v_readlane_b32 s43, v252, 23
	v_readlane_b32 s44, v252, 24
	v_readlane_b32 s45, v252, 25
	v_readlane_b32 s46, v252, 26
	v_readlane_b32 s47, v252, 27
	v_readlane_b32 s48, v252, 28
	v_readlane_b32 s49, v252, 29
	v_readlane_b32 s50, v252, 30
	v_readlane_b32 s51, v252, 31
	v_readlane_b32 s52, v252, 32
	v_readlane_b32 s53, v252, 33
	v_readlane_b32 s54, v252, 34
	v_readlane_b32 s55, v252, 35
	s_mov_b64 s[40:41], s[44:45]
	s_lshl_b64 s[14:15], s[10:11], 2
	s_mov_b64 s[42:43], s[46:47]
	s_mov_b64 s[44:45], s[48:49]
	s_mov_b64 s[46:47], s[50:51]
	s_mov_b64 s[48:49], s[52:53]
	s_add_u32 s16, s48, s14
	v_readlane_b32 s20, v252, 0
	s_addc_u32 s17, s49, s15
	v_mov_b64_e32 v[2:3], s[8:9]
	v_readlane_b32 s22, v252, 2
	v_readlane_b32 s23, v252, 3
	s_add_u32 s14, s44, s14
	s_addc_u32 s15, s45, s15
	v_lshl_add_u64 v[2:3], s[22:23], 0, v[2:3]
	s_mov_b64 s[18:19], 0x17000000
	s_ashr_i32 s1, s0, 31
	v_lshl_add_u64 v[2:3], v[2:3], 0, s[18:19]
	v_and_b32_e32 v8, 63, v0
	s_lshl_b64 s[0:1], s[0:1], 13
	v_readlane_b32 s21, v252, 1
	v_lshl_add_u64 v[0:1], v[2:3], 0, s[0:1]
	v_lshlrev_b32_e32 v160, 4, v8
	s_add_u32 s0, s20, s0
	v_lshl_add_u64 v[0:1], v[0:1], 0, v[160:161]
	s_addc_u32 s1, s21, s1
	v_lshl_add_u64 v[4:5], s[0:1], 0, v[160:161]
	global_load_dwordx4 v[124:127], v[0:1], off nt
	global_load_dwordx4 v[120:123], v[0:1], off offset:1024 nt
	global_load_dwordx4 v[92:95], v160, s[0:1] nt
	global_load_dwordx4 v[88:91], v160, s[0:1] offset:1024 nt
	global_load_dwordx4 v[116:119], v[0:1], off offset:2048 nt
	global_load_dwordx4 v[112:115], v[0:1], off offset:3072 nt
	global_load_dwordx4 v[84:87], v160, s[0:1] offset:2048 nt
	global_load_dwordx4 v[80:83], v160, s[0:1] offset:3072 nt
	s_movk_i32 s0, 0x1000
	v_add_co_u32_e32 v0, vcc, s0, v0
	v_lshl_add_u64 v[128:129], v[2:3], 0, v[160:161]
	s_nop 0
	v_addc_co_u32_e32 v1, vcc, 0, v1, vcc
	v_add_co_u32_e32 v4, vcc, s0, v4
	v_or_b32_e32 v2, 0x1400, v160
	s_nop 0
	v_addc_co_u32_e32 v5, vcc, 0, v5, vcc
	global_load_dwordx4 v[108:111], v[0:1], off nt
	global_load_dwordx4 v[104:107], v[0:1], off offset:1024 nt
	global_load_dwordx4 v[76:79], v[4:5], off nt
	global_load_dwordx4 v[72:75], v[4:5], off offset:1024 nt
	global_load_dwordx4 v[100:103], v[0:1], off offset:2048 nt
	global_load_dwordx4 v[96:99], v[0:1], off offset:3072 nt
	global_load_dwordx4 v[68:71], v[4:5], off offset:2048 nt
	global_load_dwordx4 v[64:67], v[4:5], off offset:3072 nt
	v_or_b32_e32 v0, 0x1000, v160
	v_mov_b32_e32 v1, v161
	v_mov_b32_e32 v3, v161
	v_or_b32_e32 v4, 0x1800, v160
	v_mov_b32_e32 v5, v161
	v_or_b32_e32 v6, 0x1c00, v160
	v_mov_b32_e32 v7, v161
	s_ashr_i32 s0, s12, 31
	v_readlane_b32 s1, v252, 36
	v_lshl_add_u64 v[132:133], s[14:15], 0, v[160:161]
	v_lshl_add_u64 v[134:135], s[14:15], 0, v[0:1]
	v_lshl_add_u64 v[136:137], s[14:15], 0, v[2:3]
	v_lshl_add_u64 v[138:139], s[14:15], 0, v[4:5]
	v_lshl_add_u64 v[140:141], s[14:15], 0, v[6:7]
	s_add_u32 s14, s1, s12
	v_readlane_b32 s1, v254, 48
	s_addc_u32 s15, s1, s0
	s_lshl_b64 s[0:1], s[14:15], 13
	v_readlane_b32 s13, v254, 44
	s_add_u32 s0, s13, s0
	v_readlane_b32 s13, v254, 45
	s_addc_u32 s1, s13, s1
	v_lshl_add_u64 v[152:153], s[0:1], 0, v[160:161]
	v_readlane_b32 s0, v254, 49
	s_add_i32 s0, s0, s12
	s_lshl_b64 s[12:13], s[14:15], 12
	v_lshl_add_u64 v[144:145], s[16:17], 0, v[0:1]
	v_mov_b64_e32 v[0:1], s[12:13]
	v_lshl_add_u64 v[130:131], s[20:21], 0, v[160:161]
	v_lshl_add_u64 v[142:143], s[16:17], 0, v[160:161]
	v_lshl_add_u64 v[0:1], s[8:9], 0, v[0:1]
	v_lshlrev_b32_e32 v160, 3, v8
	v_readlane_b32 s8, v254, 52
	v_lshl_add_u64 v[0:1], v[0:1], 0, v[160:161]
	v_readlane_b32 s9, v254, 53
	v_lshl_add_u64 v[146:147], s[16:17], 0, v[2:3]
	v_lshl_add_u64 v[148:149], s[16:17], 0, v[4:5]
	v_lshl_add_u64 v[150:151], s[16:17], 0, v[6:7]
	v_lshl_add_u64 v[154:155], s[8:9], 0, v[0:1]
	s_mov_b64 s[50:51], s[54:55]
	global_load_dwordx4 v[180:183], v[132:133], off
	global_load_dwordx4 v[184:187], v[132:133], off offset:1024
	global_load_dwordx4 v[188:191], v[132:133], off offset:2048
	global_load_dwordx4 v[192:195], v[132:133], off offset:3072
	global_load_dwordx4 v[196:199], v[134:135], off
	global_load_dwordx4 v[208:211], v[136:137], off
	global_load_dwordx4 v[212:215], v[138:139], off
	global_load_dwordx4 v[216:219], v[140:141], off
	global_load_dwordx4 v[220:223], v[142:143], off
	global_load_dwordx4 v[224:227], v[142:143], off offset:1024
	global_load_dwordx4 v[228:231], v[142:143], off offset:2048
	global_load_dwordx4 v[232:235], v[142:143], off offset:3072
	global_load_dwordx4 v[236:239], v[144:145], off
	global_load_dwordx4 v[240:243], v[146:147], off
	global_load_dwordx4 v[244:247], v[148:149], off
	global_load_dwordx4 v[248:251], v[150:151], off
	s_waitcnt vmcnt(0)
	s_branch .LBB0_797

; DI void resnorm_rows(const float* Y, const float* Xs, float* Xd, const float* gpost, const float* gpre, bf16* H, int gw, int NGW, int lane) {
;     ...
;         float ss = 0.f;
; #pragma unroll
;         for (int j = 0; j < 8; ++j) ss += (y[j].x * y[j].x + y[j].y * y[j].y) + (y[j].z * y[j].z + y[j].w * y[j].w);
;         const float r = rsqrtf(wave_sum(ss) * (1.f / DM) + EPS);
;         f32x4* xo = (f32x4*)(Xd + (size_t)row * DM) + lane; float s2 = 0.f;
; #pragma unroll
;         for (int j = 0; j < 8; ++j) { const f32x4 gg = ((const f32x4*)gpost)[lane + 64 * j]; x[j] = x[j] + y[j] * r * gg; __builtin_nontemporal_store(x[j], xo + 64 * j);
;             s2 += (x[j].x * x[j].x + x[j].y * x[j].y) + (x[j].z * x[j].z + x[j].w * x[j].w); }
.LBB0_799:
	v_mov_b32_e32 v158, v121
	v_mov_b32_e32 v159, v125
	v_mov_b32_e32 v156, v120
	v_mov_b32_e32 v157, v124
	v_pk_mul_f32 v[158:159], v[158:159], v[158:159]
	v_mov_b32_e32 v170, v123
	v_mov_b32_e32 v171, v127
	v_pk_fma_f32 v[156:157], v[156:157], v[156:157], v[158:159]
	v_mov_b32_e32 v158, v122
	v_mov_b32_e32 v159, v126
	v_pk_mul_f32 v[170:171], v[170:171], v[170:171]
	s_mov_b32 s1, -1
	v_pk_fma_f32 v[158:159], v[158:159], v[158:159], v[170:171]
	v_pk_mul_f32 v[170:171], v[116:117], v[116:117]
	v_pk_add_f32 v[156:157], v[156:157], v[158:159]
	v_pk_mul_f32 v[158:159], v[118:119], v[118:119]
	v_pk_add_f32 v[156:157], v[156:157], v[156:157] op_sel_hi:[0,1]
	v_pk_mov_b32 v[172:173], v[170:171], v[158:159] op_sel:[1,0]
	v_mov_b32_e32 v171, v159
	v_mul_f32_e32 v156, v112, v112
	v_pk_add_f32 v[158:159], v[172:173], v[170:171]
	v_pk_fma_f32 v[170:171], v[112:113], v[112:113], v[156:157] op_sel_hi:[1,1,0]
	v_mul_f32_e32 v156, v114, v114
	v_pk_add_f32 v[158:159], v[158:159], v[158:159] op_sel_hi:[0,1]
	v_pk_fma_f32 v[172:173], v[114:115], v[114:115], v[156:157] op_sel_hi:[1,1,0]
	v_mul_f32_e32 v170, v108, v108
	v_mul_f32_e32 v172, v109, v109
	v_mul_f32_e32 v158, v110, v110
	v_mul_f32_e32 v156, v111, v111
	v_pk_add_f32 v[170:171], v[170:171], v[172:173]
	v_pk_add_f32 v[156:157], v[158:159], v[156:157]
	v_pk_mul_f32 v[158:159], v[106:107], v[106:107]
	v_pk_add_f32 v[156:157], v[170:171], v[156:157]
	v_pk_mul_f32 v[170:171], v[104:105], v[104:105]
	v_pk_add_f32 v[156:157], v[156:157], v[156:157] op_sel_hi:[0,1]
	v_pk_mov_b32 v[172:173], v[170:171], v[158:159] op_sel:[1,0]
	v_mov_b32_e32 v171, v159
	v_mul_f32_e32 v156, v100, v100
	v_pk_add_f32 v[158:159], v[172:173], v[170:171]
	v_pk_fma_f32 v[170:171], v[100:101], v[100:101], v[156:157] op_sel_hi:[1,1,0]
	v_mul_f32_e32 v156, v102, v102
	v_pk_add_f32 v[158:159], v[158:159], v[158:159] op_sel_hi:[0,1]
	v_pk_fma_f32 v[172:173], v[102:103], v[102:103], v[156:157] op_sel_hi:[1,1,0]
	v_mul_f32_e32 v170, v96, v96
	v_mul_f32_e32 v172, v97, v97
	v_mul_f32_e32 v158, v98, v98
	v_mul_f32_e32 v156, v99, v99
	v_pk_add_f32 v[170:171], v[170:171], v[172:173]
	v_pk_add_f32 v[156:157], v[158:159], v[156:157]
	s_mov_b64 s[12:13], -1
	v_pk_add_f32 v[156:157], v[170:171], v[156:157]
	s_nop 0
	v_add_f32_e32 v156, v156, v157
	v_mbcnt_lo_u32_b32 v157, s1, 0
	v_mbcnt_hi_u32_b32 v157, s1, v157
	v_lshlrev_b32_e32 v157, 2, v157
	v_xor_b32_e32 v157, 4, v157
	ds_bpermute_b32 v157, v157, v156
	s_mov_b32 s1, -1
	s_waitcnt lgkmcnt(0)
	v_add_f32_e32 v156, v156, v157
	v_mbcnt_lo_u32_b32 v157, s1, 0
	v_mbcnt_hi_u32_b32 v157, s1, v157
	v_lshlrev_b32_e32 v157, 2, v157
	v_xor_b32_e32 v157, 8, v157
	ds_bpermute_b32 v157, v157, v156
	s_mov_b32 s1, -1
	s_waitcnt lgkmcnt(0)
	v_add_f32_e32 v156, v156, v157
	v_mbcnt_lo_u32_b32 v157, s1, 0
	v_mbcnt_hi_u32_b32 v157, s1, v157
	v_lshlrev_b32_e32 v157, 2, v157
	v_xor_b32_e32 v157, 16, v157
	ds_bpermute_b32 v157, v157, v156
	s_mov_b32 s1, -1
	s_waitcnt lgkmcnt(0)
	v_add_f32_e32 v156, v156, v157
	v_mbcnt_lo_u32_b32 v157, s1, 0
	v_mbcnt_hi_u32_b32 v157, s1, v157
	v_lshlrev_b32_e32 v157, 2, v157
	v_xor_b32_e32 v157, 32, v157
	ds_bpermute_b32 v157, v157, v156
	s_mov_b32 s1, -1
	s_waitcnt lgkmcnt(0)
	v_add_f32_e32 v156, v156, v157
	v_mbcnt_lo_u32_b32 v157, s1, 0
	v_mbcnt_hi_u32_b32 v157, s1, v157
	s_mov_b32 s1, -1
	v_lshlrev_b32_e32 v157, 2, v157
	v_xor_b32_e32 v157, 64, v157
	ds_bpermute_b32 v157, v157, v156
	s_waitcnt lgkmcnt(0)
	v_add_f32_e32 v156, v156, v157
	v_mbcnt_lo_u32_b32 v157, s1, 0
	v_mbcnt_hi_u32_b32 v157, s1, v157
	v_lshlrev_b32_e32 v157, 2, v157
	v_xor_b32_e32 v157, 0x80, v157
	ds_bpermute_b32 v157, v157, v156
	s_mov_b32 s1, -1
	s_waitcnt lgkmcnt(0)
	v_add_f32_e32 v156, v156, v157
	v_fmamk_f32 v156, v156, 0x3a000000, v203
	v_cmp_gt_f32_e32 vcc, s2, v156
	v_mul_f32_e32 v157, 0x4b800000, v156
	s_nop 0
	v_cndmask_b32_e32 v156, v156, v157, vcc
	v_rsq_f32_e32 v156, v156
	s_nop 0
	v_mul_f32_e32 v157, 0x45800000, v156
	v_cndmask_b32_e32 v156, v156, v157, vcc
	v_pk_mul_f32 v[124:125], v[124:125], v[156:157] op_sel_hi:[1,0]
	v_pk_mul_f32 v[126:127], v[126:127], v[156:157] op_sel_hi:[1,0]
	v_pk_mul_f32 v[122:123], v[122:123], v[156:157] op_sel_hi:[1,0]
	v_pk_mul_f32 v[120:121], v[120:121], v[156:157] op_sel_hi:[1,0]
	v_pk_mul_f32 v[118:119], v[118:119], v[156:157] op_sel_hi:[1,0]
	v_pk_mul_f32 v[116:117], v[116:117], v[156:157] op_sel_hi:[1,0]
	v_pk_mul_f32 v[114:115], v[114:115], v[156:157] op_sel_hi:[1,0]
	v_pk_mul_f32 v[112:113], v[112:113], v[156:157] op_sel_hi:[1,0]
	v_pk_mul_f32 v[108:109], v[108:109], v[156:157] op_sel_hi:[1,0]
	v_pk_mul_f32 v[110:111], v[110:111], v[156:157] op_sel_hi:[1,0]
	v_pk_mul_f32 v[106:107], v[106:107], v[156:157] op_sel_hi:[1,0]
	v_pk_mul_f32 v[104:105], v[104:105], v[156:157] op_sel_hi:[1,0]
	v_pk_mul_f32 v[102:103], v[102:103], v[156:157] op_sel_hi:[1,0]
	v_pk_mul_f32 v[100:101], v[100:101], v[156:157] op_sel_hi:[1,0]
	v_pk_mul_f32 v[98:99], v[98:99], v[156:157] op_sel_hi:[1,0]
	v_pk_mul_f32 v[96:97], v[96:97], v[156:157] op_sel_hi:[1,0]
	v_pk_fma_f32 v[94:95], v[182:183], v[126:127], v[94:95]
	v_pk_fma_f32 v[92:93], v[180:181], v[124:125], v[92:93]
	global_store_dwordx4 v[152:153], v[92:95], off offset:-4096 nt
	v_pk_fma_f32 v[88:89], v[184:185], v[120:121], v[88:89]
	v_pk_fma_f32 v[90:91], v[186:187], v[122:123], v[90:91]
	global_store_dwordx4 v[152:153], v[88:91], off offset:-3072 nt
	v_pk_fma_f32 v[84:85], v[188:189], v[116:117], v[84:85]
	v_pk_fma_f32 v[86:87], v[190:191], v[118:119], v[86:87]
	global_store_dwordx4 v[152:153], v[84:87], off offset:-2048 nt
	v_pk_fma_f32 v[80:81], v[192:193], v[112:113], v[80:81]
	v_pk_fma_f32 v[82:83], v[194:195], v[114:115], v[82:83]
; DI void resnorm_rows(const float* Y, const float* Xs, float* Xd, const float* gpost, const float* gpre, bf16* H, int gw, int NGW, int lane) {
;     ...
;         for (int j = 0; j < 8; ++j) { const f32x4 gg = ((const f32x4*)gpost)[lane + 64 * j]; x[j] = x[j] + y[j] * r * gg; __builtin_nontemporal_store(x[j], xo + 64 * j);
;             s2 += (x[j].x * x[j].x + x[j].y * x[j].y) + (x[j].z * x[j].z + x[j].w * x[j].w); }
;         if (H) {
;             const float r2 = rsqrtf(wave_sum(s2) * (1.f / DM) + EPS);
	global_store_dwordx4 v[152:153], v[80:83], off offset:-1024 nt
	v_pk_fma_f32 v[78:79], v[198:199], v[110:111], v[78:79]
	v_pk_fma_f32 v[76:77], v[196:197], v[108:109], v[76:77]
	global_store_dwordx4 v[152:153], v[76:79], off nt
	v_pk_fma_f32 v[72:73], v[208:209], v[104:105], v[72:73]
	v_pk_fma_f32 v[74:75], v[210:211], v[106:107], v[74:75]
	global_store_dwordx4 v[152:153], v[72:75], off offset:1024 nt
	v_pk_fma_f32 v[68:69], v[100:101], v[212:213], v[68:69]
	v_pk_fma_f32 v[70:71], v[102:103], v[214:215], v[70:71]
	global_store_dwordx4 v[152:153], v[68:71], off offset:2048 nt
	v_pk_fma_f32 v[66:67], v[98:99], v[218:219], v[66:67]
	v_mov_b32_e32 v98, v93
	v_mov_b32_e32 v99, v89
	v_pk_fma_f32 v[64:65], v[96:97], v[216:217], v[64:65]
	v_mov_b32_e32 v96, v92
	v_mov_b32_e32 v97, v88
	v_pk_mul_f32 v[98:99], v[98:99], v[98:99]
	v_mov_b32_e32 v100, v95
	v_mov_b32_e32 v101, v91
	v_pk_fma_f32 v[96:97], v[96:97], v[96:97], v[98:99]
	v_mov_b32_e32 v98, v94
	v_mov_b32_e32 v99, v90
	v_pk_mul_f32 v[100:101], v[100:101], v[100:101]
	global_store_dwordx4 v[152:153], v[64:67], off offset:3072 nt
	v_pk_fma_f32 v[98:99], v[98:99], v[98:99], v[100:101]
	v_pk_mul_f32 v[100:101], v[86:87], v[86:87]
	v_pk_add_f32 v[96:97], v[96:97], v[98:99]
	v_pk_mul_f32 v[98:99], v[84:85], v[84:85]
	v_pk_add_f32 v[96:97], v[96:97], v[96:97] op_sel_hi:[0,1]
	v_pk_mov_b32 v[102:103], v[98:99], v[100:101] op_sel:[1,0]
	v_mov_b32_e32 v99, v101
	v_mul_f32_e32 v96, v80, v80
	v_pk_add_f32 v[98:99], v[102:103], v[98:99]
	v_pk_fma_f32 v[100:101], v[80:81], v[80:81], v[96:97] op_sel_hi:[1,1,0]
	v_mul_f32_e32 v96, v82, v82
	v_pk_add_f32 v[98:99], v[98:99], v[98:99] op_sel_hi:[0,1]
	v_pk_fma_f32 v[102:103], v[82:83], v[82:83], v[96:97] op_sel_hi:[1,1,0]
	v_mul_f32_e32 v100, v76, v76
	v_mul_f32_e32 v102, v77, v77
	v_mul_f32_e32 v98, v78, v78
	v_mul_f32_e32 v96, v79, v79
	v_pk_add_f32 v[100:101], v[100:101], v[102:103]
	v_pk_add_f32 v[96:97], v[98:99], v[96:97]
	v_pk_mul_f32 v[98:99], v[72:73], v[72:73]
	v_pk_add_f32 v[96:97], v[100:101], v[96:97]
	v_pk_mul_f32 v[100:101], v[74:75], v[74:75]
	v_pk_add_f32 v[96:97], v[96:97], v[96:97] op_sel_hi:[0,1]
	v_pk_mov_b32 v[102:103], v[98:99], v[100:101] op_sel:[1,0]
	v_mov_b32_e32 v99, v101
	v_mul_f32_e32 v96, v68, v68
	v_pk_add_f32 v[98:99], v[102:103], v[98:99]
	v_pk_fma_f32 v[100:101], v[68:69], v[68:69], v[96:97] op_sel_hi:[1,1,0]
	v_mul_f32_e32 v96, v70, v70
	v_pk_add_f32 v[98:99], v[98:99], v[98:99] op_sel_hi:[0,1]
	v_pk_fma_f32 v[102:103], v[70:71], v[70:71], v[96:97] op_sel_hi:[1,1,0]
	v_mul_f32_e32 v100, v64, v64
	v_mul_f32_e32 v102, v65, v65
	v_mul_f32_e32 v98, v66, v66
	v_mul_f32_e32 v96, v67, v67
	v_pk_add_f32 v[100:101], v[100:101], v[102:103]
	v_pk_add_f32 v[96:97], v[98:99], v[96:97]
	s_nop 0
	v_pk_add_f32 v[96:97], v[100:101], v[96:97]
	s_nop 0
	v_add_f32_e32 v96, v96, v97
	v_mbcnt_lo_u32_b32 v97, s1, 0
	v_mbcnt_hi_u32_b32 v97, s1, v97
	v_lshlrev_b32_e32 v97, 2, v97
	v_xor_b32_e32 v97, 4, v97
	ds_bpermute_b32 v97, v97, v96
	s_mov_b32 s1, -1
	s_waitcnt lgkmcnt(0)
	v_add_f32_e32 v96, v96, v97
	v_mbcnt_lo_u32_b32 v97, s1, 0
	v_mbcnt_hi_u32_b32 v97, s1, v97
	v_lshlrev_b32_e32 v97, 2, v97
	v_xor_b32_e32 v97, 8, v97
	ds_bpermute_b32 v97, v97, v96
	s_mov_b32 s1, -1
	s_waitcnt lgkmcnt(0)
	v_add_f32_e32 v96, v96, v97
	v_mbcnt_lo_u32_b32 v97, s1, 0
	v_mbcnt_hi_u32_b32 v97, s1, v97
	v_lshlrev_b32_e32 v97, 2, v97
	v_xor_b32_e32 v97, 16, v97
	ds_bpermute_b32 v97, v97, v96
	s_mov_b32 s1, -1
	s_waitcnt lgkmcnt(0)
	v_add_f32_e32 v96, v96, v97
	v_mbcnt_lo_u32_b32 v97, s1, 0
	v_mbcnt_hi_u32_b32 v97, s1, v97
	v_lshlrev_b32_e32 v97, 2, v97
	v_xor_b32_e32 v97, 32, v97
	ds_bpermute_b32 v97, v97, v96
	s_mov_b32 s1, -1
	s_waitcnt lgkmcnt(0)
	v_add_f32_e32 v96, v96, v97
	v_mbcnt_lo_u32_b32 v97, s1, 0
	v_mbcnt_hi_u32_b32 v97, s1, v97
	v_lshlrev_b32_e32 v97, 2, v97
	v_xor_b32_e32 v97, 64, v97
	ds_bpermute_b32 v97, v97, v96
	s_mov_b32 s1, -1
	s_waitcnt lgkmcnt(0)
	v_add_f32_e32 v96, v96, v97
	v_mbcnt_lo_u32_b32 v97, s1, 0
	v_mbcnt_hi_u32_b32 v97, s1, v97
	v_lshlrev_b32_e32 v97, 2, v97
	v_xor_b32_e32 v97, 0x80, v97
	ds_bpermute_b32 v97, v97, v96
	s_waitcnt lgkmcnt(0)
; DI unsigned pk2(float lo, float hi) { f32x2_t v = {lo, hi}; bf16x2_t b = __builtin_convertvector(v, bf16x2_t); return __builtin_bit_cast(unsigned, b); }
; DI void resnorm_rows(const float* Y, const float* Xs, float* Xd, const float* gpost, const float* gpre, bf16* H, int gw, int NGW, int lane) {
;     ...
;             const float r2 = rsqrtf(wave_sum(s2) * (1.f / DM) + EPS);
;             u32x2* o = (u32x2*)(H + (size_t)row * DM) + lane;
; #pragma unroll
;             for (int j = 0; j < 8; ++j) { const f32x4 gg = ((const f32x4*)gpre)[lane + 64 * j]; u32x2 w; w.x = pk2(x[j].x * r2 * gg.x, x[j].y * r2 * gg.y); w.y = pk2(x[j].z * r2 * gg.z, x[j].w * r2 * gg.w); o[64 * j] = w; }
;         }
;         if (!has) break;
; #pragma unroll
;         for (int j = 0; j < 8; ++j) { y[j] = yn[j]; x[j] = xn[j]; }
;         row = nrow;
	v_add_f32_e32 v96, v96, v97
	v_fmamk_f32 v96, v96, 0x3a000000, v203
	v_cmp_gt_f32_e32 vcc, s2, v96
	v_mul_f32_e32 v97, 0x4b800000, v96
	s_nop 0
	v_cndmask_b32_e32 v96, v96, v97, vcc
	v_rsq_f32_e32 v96, v96
	s_nop 0
	v_mul_f32_e32 v97, 0x45800000, v96
	v_cndmask_b32_e32 v100, v96, v97, vcc
	v_pk_mul_f32 v[92:93], v[92:93], v[100:101] op_sel_hi:[1,0]
	v_pk_mul_f32 v[94:95], v[94:95], v[100:101] op_sel_hi:[1,0]
	v_pk_mul_f32 v[88:89], v[88:89], v[100:101] op_sel_hi:[1,0]
	v_pk_mul_f32 v[90:91], v[90:91], v[100:101] op_sel_hi:[1,0]
	v_pk_mul_f32 v[84:85], v[84:85], v[100:101] op_sel_hi:[1,0]
	v_pk_mul_f32 v[86:87], v[86:87], v[100:101] op_sel_hi:[1,0]
	v_pk_mul_f32 v[80:81], v[80:81], v[100:101] op_sel_hi:[1,0]
	v_pk_mul_f32 v[82:83], v[82:83], v[100:101] op_sel_hi:[1,0]
	v_pk_mul_f32 v[76:77], v[76:77], v[100:101] op_sel_hi:[1,0]
	v_pk_mul_f32 v[78:79], v[78:79], v[100:101] op_sel_hi:[1,0]
	v_pk_mul_f32 v[72:73], v[72:73], v[100:101] op_sel_hi:[1,0]
	v_pk_mul_f32 v[74:75], v[74:75], v[100:101] op_sel_hi:[1,0]
	v_pk_mul_f32 v[68:69], v[68:69], v[100:101] op_sel_hi:[1,0]
	v_pk_mul_f32 v[70:71], v[70:71], v[100:101] op_sel_hi:[1,0]
	v_pk_mul_f32 v[64:65], v[64:65], v[100:101] op_sel_hi:[1,0]
	v_pk_mul_f32 v[66:67], v[66:67], v[100:101] op_sel_hi:[1,0]
	s_andn2_b64 vcc, exec, s[8:9]
	v_pk_mul_f32 v[92:93], v[220:221], v[92:93]
	v_pk_mul_f32 v[94:95], v[222:223], v[94:95]
	v_cvt_pk_bf16_f32 v92, v92, v93
	v_cvt_pk_bf16_f32 v93, v94, v95
	global_store_dwordx2 v[154:155], v[92:93], off offset:-2048
	v_pk_mul_f32 v[88:89], v[224:225], v[88:89]
	v_pk_mul_f32 v[90:91], v[226:227], v[90:91]
	v_cvt_pk_bf16_f32 v88, v88, v89
	v_cvt_pk_bf16_f32 v89, v90, v91
	global_store_dwordx2 v[154:155], v[88:89], off offset:-1536
	v_pk_mul_f32 v[84:85], v[228:229], v[84:85]
	v_pk_mul_f32 v[86:87], v[230:231], v[86:87]
	v_cvt_pk_bf16_f32 v84, v84, v85
	v_cvt_pk_bf16_f32 v85, v86, v87
	global_store_dwordx2 v[154:155], v[84:85], off offset:-1024
	v_pk_mul_f32 v[80:81], v[232:233], v[80:81]
	v_pk_mul_f32 v[82:83], v[234:235], v[82:83]
	v_cvt_pk_bf16_f32 v80, v80, v81
	v_cvt_pk_bf16_f32 v81, v82, v83
	global_store_dwordx2 v[154:155], v[80:81], off offset:-512
	v_pk_mul_f32 v[76:77], v[76:77], v[236:237]
	v_pk_mul_f32 v[78:79], v[78:79], v[238:239]
	v_cvt_pk_bf16_f32 v76, v76, v77
	v_cvt_pk_bf16_f32 v77, v78, v79
	global_store_dwordx2 v[154:155], v[76:77], off
	v_pk_mul_f32 v[72:73], v[72:73], v[240:241]
	v_pk_mul_f32 v[74:75], v[74:75], v[242:243]
	v_cvt_pk_bf16_f32 v72, v72, v73
	v_cvt_pk_bf16_f32 v73, v74, v75
	global_store_dwordx2 v[154:155], v[72:73], off offset:512
	v_pk_mul_f32 v[68:69], v[68:69], v[244:245]
	v_pk_mul_f32 v[70:71], v[70:71], v[246:247]
	v_cvt_pk_bf16_f32 v68, v68, v69
	v_cvt_pk_bf16_f32 v69, v70, v71
	global_store_dwordx2 v[154:155], v[68:69], off offset:1024
	v_pk_mul_f32 v[64:65], v[64:65], v[248:249]
	v_pk_mul_f32 v[66:67], v[66:67], v[250:251]
	v_cvt_pk_bf16_f32 v64, v64, v65
	v_cvt_pk_bf16_f32 v65, v66, v67
	global_store_dwordx2 v[154:155], v[64:65], off offset:1536
	s_cbranch_vccnz .LBB0_796
	s_waitcnt vmcnt(16)
	v_readlane_b32 s8, v254, 50
	v_readlane_b32 s9, v254, 51
	s_add_i32 s0, s0, s62
	s_mov_b64 s[12:13], 0
	v_lshl_add_u64 v[152:153], v[152:153], 0, s[8:9]
	v_readlane_b32 s8, v254, 54
	v_readlane_b32 s9, v254, 55
	v_mov_b32_e32 v67, v59
	v_mov_b32_e32 v66, v58
	v_lshl_add_u64 v[154:155], v[154:155], 0, s[8:9]
	v_mov_b32_e32 v65, v57
	v_mov_b32_e32 v64, v56
	v_mov_b32_e32 v71, v63
	v_mov_b32_e32 v70, v62
	v_mov_b32_e32 v69, v61
	v_mov_b32_e32 v68, v60
	v_mov_b32_e32 v75, v51
	v_mov_b32_e32 v74, v50
	v_mov_b32_e32 v73, v49
	v_mov_b32_e32 v72, v48
	v_mov_b32_e32 v79, v55
	v_mov_b32_e32 v78, v54
	v_mov_b32_e32 v77, v53
	v_mov_b32_e32 v76, v52
	v_mov_b32_e32 v83, v27
	v_mov_b32_e32 v82, v26
	v_mov_b32_e32 v81, v25
	v_mov_b32_e32 v80, v24
	v_mov_b32_e32 v87, v31
	v_mov_b32_e32 v86, v30
	v_mov_b32_e32 v85, v29
	v_mov_b32_e32 v84, v28
	v_mov_b32_e32 v91, v19
	v_mov_b32_e32 v90, v18
	v_mov_b32_e32 v89, v17
	v_mov_b32_e32 v88, v16
	v_mov_b32_e32 v95, v23
	v_mov_b32_e32 v94, v22
	v_mov_b32_e32 v93, v21
	v_mov_b32_e32 v92, v20
	s_branch .LBB0_796

; DI void resnorm_rows(const float* Y, const float* Xs, float* Xd, const float* gpost, const float* gpre, bf16* H, int gw, int NGW, int lane) {
;     int row = gw; if (row >= T) return;
;     f32x4 y[8], x[8], yn[8], xn[8];
;     { const f32x4* yr = (const f32x4*)(Y + (size_t)row * DM) + lane; const f32x4* xr = (const f32x4*)(Xs + (size_t)row * DM) + lane;
; #pragma unroll
;       for (int j = 0; j < 8; ++j) { y[j] = __builtin_nontemporal_load(yr + 64 * j); x[j] = __builtin_nontemporal_load(xr + 64 * j); } }
;     for (;;) {
;         const int nrow = row + NGW; const bool has = nrow < T;
;         if (has) { const f32x4* yr = (const f32x4*)(Y + (size_t)nrow * DM) + lane; const f32x4* xr = (const f32x4*)(Xs + (size_t)nrow * DM) + lane;
; #pragma unroll
;             for (int j = 0; j < 8; ++j) { yn[j] = __builtin_nontemporal_load(yr + 64 * j); xn[j] = __builtin_nontemporal_load(xr + 64 * j); } }
;     ...
;         for (int j = 0; j < 8; ++j) { const f32x4 gg = ((const f32x4*)gpost)[lane + 64 * j]; x[j] = x[j] + y[j] * r * gg; __builtin_nontemporal_store(x[j], xo + 64 * j);
.LBB0_999:
	s_or_b64 exec, exec, s[0:1]
	v_readlane_b32 s4, v255, 5
	v_readlane_b32 s5, v255, 6
	s_mov_b64 s[0:1], -1
	s_and_b64 vcc, exec, s[4:5]
	s_waitcnt lgkmcnt(0)
	s_barrier
	s_cbranch_vccz .LBB0_1008
	s_mov_b32 s0, -1
	s_mov_b64 s[4:5], 0
	v_mbcnt_lo_u32_b32 v0, s0, 0
	v_mbcnt_hi_u32_b32 v0, s0, v0
	v_add_u32_e32 v0, s68, v0
	s_nop 0
	v_readfirstlane_b32 s0, v0
	s_ashr_i32 s6, s0, 6
	v_readlane_b32 s0, v252, 36
	s_add_i32 s0, s6, s0
	s_cmpk_gt_i32 s0, 0x3fff
	s_cbranch_scc1 .LBB0_1007
	v_readlane_b32 s12, v252, 20
	v_readlane_b32 s13, v252, 21
	v_readlane_b32 s14, v252, 22
	v_readlane_b32 s15, v252, 23
	v_readlane_b32 s16, v252, 24
	v_readlane_b32 s17, v252, 25
	v_readlane_b32 s18, v252, 26
	v_readlane_b32 s19, v252, 27
	v_readlane_b32 s20, v252, 28
	v_readlane_b32 s21, v252, 29
	v_readlane_b32 s22, v252, 30
	v_readlane_b32 s23, v252, 31
	v_readlane_b32 s24, v252, 32
	v_readlane_b32 s25, v252, 33
	v_readlane_b32 s26, v252, 34
	v_readlane_b32 s27, v252, 35
	s_mov_b64 s[12:13], s[16:17]
	s_mov_b64 s[14:15], s[18:19]
	s_lshl_b64 s[8:9], s[10:11], 2
	s_mov_b64 s[16:17], s[20:21]
	s_mov_b64 s[18:19], s[22:23]
	s_mov_b64 s[20:21], s[24:25]
	s_mov_b64 s[22:23], s[26:27]
	v_readlane_b32 s12, v252, 0
	s_add_u32 s8, s22, s8
	v_mov_b64_e32 v[2:3], s[4:5]
	v_readlane_b32 s14, v252, 2
	v_readlane_b32 s15, v252, 3
	s_addc_u32 s9, s23, s9
	s_mov_b64 s[4:5], 0x17000000
	v_lshl_add_u64 v[2:3], s[14:15], 0, v[2:3]
	s_ashr_i32 s1, s0, 31
	v_lshl_add_u64 v[2:3], v[2:3], 0, s[4:5]
	v_and_b32_e32 v4, 63, v0
	s_lshl_b64 s[0:1], s[0:1], 13
	v_readlane_b32 s13, v252, 1
	v_lshl_add_u64 v[0:1], v[2:3], 0, s[0:1]
	v_lshlrev_b32_e32 v160, 4, v4
	s_add_u32 s0, s12, s0
	v_lshl_add_u64 v[0:1], v[0:1], 0, v[160:161]
	s_addc_u32 s1, s13, s1
	v_lshl_add_u64 v[4:5], s[0:1], 0, v[160:161]
	global_load_dwordx4 v[124:127], v[0:1], off nt
	global_load_dwordx4 v[120:123], v[0:1], off offset:1024 nt
	global_load_dwordx4 v[100:103], v160, s[0:1] nt
	global_load_dwordx4 v[92:95], v160, s[0:1] offset:1024 nt
	global_load_dwordx4 v[116:119], v[0:1], off offset:2048 nt
	global_load_dwordx4 v[112:115], v[0:1], off offset:3072 nt
	global_load_dwordx4 v[84:87], v160, s[0:1] offset:2048 nt
	global_load_dwordx4 v[80:83], v160, s[0:1] offset:3072 nt
	s_movk_i32 s0, 0x1000
	v_add_co_u32_e32 v0, vcc, s0, v0
	v_lshl_add_u64 v[132:133], s[8:9], 0, v[160:161]
	s_nop 0
	v_addc_co_u32_e32 v1, vcc, 0, v1, vcc
	v_add_co_u32_e32 v4, vcc, s0, v4
	s_mov_b64 s[0:1], 0x1400
	s_nop 0
	v_addc_co_u32_e32 v5, vcc, 0, v5, vcc
	global_load_dwordx4 v[108:111], v[0:1], off nt
	global_load_dwordx4 v[104:107], v[0:1], off offset:1024 nt
	global_load_dwordx4 v[76:79], v[4:5], off nt
	global_load_dwordx4 v[72:75], v[4:5], off offset:1024 nt
	global_load_dwordx4 v[96:99], v[0:1], off offset:2048 nt
	global_load_dwordx4 v[88:91], v[0:1], off offset:3072 nt
	global_load_dwordx4 v[68:71], v[4:5], off offset:2048 nt
	global_load_dwordx4 v[36:39], v[4:5], off offset:3072 nt
	v_lshl_add_u64 v[136:137], v[132:133], 0, s[0:1]
	s_mov_b64 s[0:1], 0x1800
	v_lshl_add_u64 v[138:139], v[132:133], 0, s[0:1]
	s_mov_b64 s[0:1], 0x1c00
	v_lshl_add_u64 v[140:141], v[132:133], 0, s[0:1]
	s_ashr_i32 s1, s6, 31
	v_readlane_b32 s0, v252, 36
	s_add_u32 s0, s0, s6
	v_readlane_b32 s4, v254, 48
	s_addc_u32 s1, s4, s1
	s_lshl_b64 s[0:1], s[0:1], 13
	v_readlane_b32 s4, v254, 44
	s_add_u32 s0, s4, s0
	v_readlane_b32 s4, v254, 45
	s_addc_u32 s1, s4, s1
	v_lshl_add_u64 v[142:143], s[0:1], 0, v[160:161]
	v_readlane_b32 s0, v254, 49
	v_lshl_add_u64 v[128:129], v[2:3], 0, v[160:161]
	v_lshl_add_u64 v[130:131], s[12:13], 0, v[160:161]
	v_lshl_add_u64 v[134:135], v[132:133], 0, s[76:77]
	s_add_i32 s0, s0, s6
	global_load_dwordx4 v[180:183], v[132:133], off
	global_load_dwordx4 v[184:187], v[132:133], off offset:1024
	global_load_dwordx4 v[188:191], v[132:133], off offset:2048
	global_load_dwordx4 v[192:195], v[132:133], off offset:3072
	global_load_dwordx4 v[196:199], v[134:135], off
	global_load_dwordx4 v[208:211], v[136:137], off
	global_load_dwordx4 v[212:215], v[138:139], off
	global_load_dwordx4 v[216:219], v[140:141], off
	s_waitcnt vmcnt(0)
	s_branch .LBB0_1003

; DI void resnorm_rows(const float* Y, const float* Xs, float* Xd, const float* gpost, const float* gpre, bf16* H, int gw, int NGW, int lane) {
;     ...
;         float ss = 0.f;
; #pragma unroll
;         for (int j = 0; j < 8; ++j) ss += (y[j].x * y[j].x + y[j].y * y[j].y) + (y[j].z * y[j].z + y[j].w * y[j].w);
;         const float r = rsqrtf(wave_sum(ss) * (1.f / DM) + EPS);
;         f32x4* xo = (f32x4*)(Xd + (size_t)row * DM) + lane; float s2 = 0.f;
; #pragma unroll
;         for (int j = 0; j < 8; ++j) { const f32x4 gg = ((const f32x4*)gpost)[lane + 64 * j]; x[j] = x[j] + y[j] * r * gg; __builtin_nontemporal_store(x[j], xo + 64 * j);
;             s2 += (x[j].x * x[j].x + x[j].y * x[j].y) + (x[j].z * x[j].z + x[j].w * x[j].w); }
.LBB0_1005:
	v_mov_b32_e32 v146, v121
	v_mov_b32_e32 v147, v125
	v_mov_b32_e32 v144, v120
	v_mov_b32_e32 v145, v124
	v_pk_mul_f32 v[146:147], v[146:147], v[146:147]
	v_mov_b32_e32 v148, v123
	v_mov_b32_e32 v149, v127
	v_pk_fma_f32 v[144:145], v[144:145], v[144:145], v[146:147]
	v_mov_b32_e32 v146, v122
	v_mov_b32_e32 v147, v126
	v_pk_mul_f32 v[148:149], v[148:149], v[148:149]
	s_mov_b32 s1, -1
	v_pk_fma_f32 v[146:147], v[146:147], v[146:147], v[148:149]
	v_pk_mul_f32 v[148:149], v[116:117], v[116:117]
	v_pk_add_f32 v[144:145], v[144:145], v[146:147]
	v_pk_mul_f32 v[146:147], v[118:119], v[118:119]
	v_pk_add_f32 v[144:145], v[144:145], v[144:145] op_sel_hi:[0,1]
	v_pk_mov_b32 v[150:151], v[148:149], v[146:147] op_sel:[1,0]
	v_mov_b32_e32 v149, v147
	v_mul_f32_e32 v144, v112, v112
	v_pk_add_f32 v[146:147], v[150:151], v[148:149]
	v_pk_fma_f32 v[148:149], v[112:113], v[112:113], v[144:145] op_sel_hi:[1,1,0]
	v_mul_f32_e32 v144, v114, v114
	v_pk_add_f32 v[146:147], v[146:147], v[146:147] op_sel_hi:[0,1]
	v_pk_fma_f32 v[150:151], v[114:115], v[114:115], v[144:145] op_sel_hi:[1,1,0]
	v_mul_f32_e32 v148, v108, v108
	v_mul_f32_e32 v150, v109, v109
	v_mul_f32_e32 v146, v110, v110
	v_mul_f32_e32 v144, v111, v111
	v_pk_add_f32 v[148:149], v[148:149], v[150:151]
	v_pk_add_f32 v[144:145], v[146:147], v[144:145]
	v_pk_mul_f32 v[146:147], v[106:107], v[106:107]
	v_pk_add_f32 v[144:145], v[148:149], v[144:145]
	v_pk_mul_f32 v[148:149], v[104:105], v[104:105]
	v_pk_add_f32 v[144:145], v[144:145], v[144:145] op_sel_hi:[0,1]
	v_pk_mov_b32 v[150:151], v[148:149], v[146:147] op_sel:[1,0]
	v_mov_b32_e32 v149, v147
	v_mul_f32_e32 v144, v96, v96
	v_pk_add_f32 v[146:147], v[150:151], v[148:149]
	v_pk_fma_f32 v[148:149], v[96:97], v[96:97], v[144:145] op_sel_hi:[1,1,0]
	v_mul_f32_e32 v144, v98, v98
	v_pk_add_f32 v[146:147], v[146:147], v[146:147] op_sel_hi:[0,1]
	v_pk_fma_f32 v[150:151], v[98:99], v[98:99], v[144:145] op_sel_hi:[1,1,0]
	v_mul_f32_e32 v148, v88, v88
	v_mul_f32_e32 v150, v89, v89
	v_mul_f32_e32 v146, v90, v90
	v_mul_f32_e32 v144, v91, v91
	v_pk_add_f32 v[148:149], v[148:149], v[150:151]
	v_pk_add_f32 v[144:145], v[146:147], v[144:145]
	s_mov_b64 s[6:7], -1
	v_pk_add_f32 v[144:145], v[148:149], v[144:145]
	s_nop 0
	v_add_f32_e32 v144, v144, v145
	v_mbcnt_lo_u32_b32 v145, s1, 0
	v_mbcnt_hi_u32_b32 v145, s1, v145
	v_lshlrev_b32_e32 v145, 2, v145
	v_xor_b32_e32 v145, 4, v145
	ds_bpermute_b32 v145, v145, v144
	s_mov_b32 s1, -1
	s_waitcnt lgkmcnt(0)
	v_add_f32_e32 v144, v144, v145
	v_mbcnt_lo_u32_b32 v145, s1, 0
	v_mbcnt_hi_u32_b32 v145, s1, v145
	v_lshlrev_b32_e32 v145, 2, v145
	v_xor_b32_e32 v145, 8, v145
	ds_bpermute_b32 v145, v145, v144
	s_mov_b32 s1, -1
	s_waitcnt lgkmcnt(0)
	v_add_f32_e32 v144, v144, v145
	v_mbcnt_lo_u32_b32 v145, s1, 0
	v_mbcnt_hi_u32_b32 v145, s1, v145
	v_lshlrev_b32_e32 v145, 2, v145
	v_xor_b32_e32 v145, 16, v145
	ds_bpermute_b32 v145, v145, v144
	s_mov_b32 s1, -1
	s_waitcnt lgkmcnt(0)
	v_add_f32_e32 v144, v144, v145
	v_mbcnt_lo_u32_b32 v145, s1, 0
	v_mbcnt_hi_u32_b32 v145, s1, v145
	v_lshlrev_b32_e32 v145, 2, v145
	v_xor_b32_e32 v145, 32, v145
	ds_bpermute_b32 v145, v145, v144
	s_mov_b32 s1, -1
	s_waitcnt lgkmcnt(0)
	v_add_f32_e32 v144, v144, v145
	v_mbcnt_lo_u32_b32 v145, s1, 0
	v_mbcnt_hi_u32_b32 v145, s1, v145
	s_mov_b32 s1, -1
	v_lshlrev_b32_e32 v145, 2, v145
	v_xor_b32_e32 v145, 64, v145
	ds_bpermute_b32 v145, v145, v144
	s_waitcnt lgkmcnt(0)
	v_add_f32_e32 v144, v144, v145
	v_mbcnt_lo_u32_b32 v145, s1, 0
	v_mbcnt_hi_u32_b32 v145, s1, v145
	v_lshlrev_b32_e32 v145, 2, v145
	v_xor_b32_e32 v145, 0x80, v145
	ds_bpermute_b32 v145, v145, v144
	s_waitcnt lgkmcnt(0)
	v_add_f32_e32 v144, v144, v145
	v_fmamk_f32 v144, v144, 0x3a000000, v203
	v_cmp_gt_f32_e32 vcc, s2, v144
	v_mul_f32_e32 v145, 0x4b800000, v144
	s_nop 0
	v_cndmask_b32_e32 v144, v144, v145, vcc
	v_rsq_f32_e32 v144, v144
	s_nop 0
	v_mul_f32_e32 v145, 0x45800000, v144
	v_cndmask_b32_e32 v144, v144, v145, vcc
	v_pk_mul_f32 v[124:125], v[124:125], v[144:145] op_sel_hi:[1,0]
	v_pk_mul_f32 v[126:127], v[126:127], v[144:145] op_sel_hi:[1,0]
	v_pk_mul_f32 v[122:123], v[122:123], v[144:145] op_sel_hi:[1,0]
	v_pk_mul_f32 v[120:121], v[120:121], v[144:145] op_sel_hi:[1,0]
	s_andn2_b64 vcc, exec, s[4:5]
	v_pk_fma_f32 v[102:103], v[182:183], v[126:127], v[102:103]
	v_pk_fma_f32 v[100:101], v[180:181], v[124:125], v[100:101]
	global_store_dwordx4 v[142:143], v[100:103], off offset:-4096 nt
	v_pk_fma_f32 v[92:93], v[184:185], v[120:121], v[92:93]
	v_pk_fma_f32 v[94:95], v[186:187], v[122:123], v[94:95]
	global_store_dwordx4 v[142:143], v[92:95], off offset:-3072 nt
	v_pk_mul_f32 v[100:101], v[118:119], v[144:145] op_sel_hi:[1,0]
	v_pk_mul_f32 v[102:103], v[116:117], v[144:145] op_sel_hi:[1,0]
	v_pk_fma_f32 v[86:87], v[190:191], v[100:101], v[86:87]
	v_pk_fma_f32 v[84:85], v[188:189], v[102:103], v[84:85]
	global_store_dwordx4 v[142:143], v[84:87], off offset:-2048 nt
	v_pk_mul_f32 v[92:93], v[114:115], v[144:145] op_sel_hi:[1,0]
	v_pk_mul_f32 v[94:95], v[112:113], v[144:145] op_sel_hi:[1,0]
	v_pk_fma_f32 v[82:83], v[194:195], v[92:93], v[82:83]
	v_pk_fma_f32 v[80:81], v[192:193], v[94:95], v[80:81]
	global_store_dwordx4 v[142:143], v[80:83], off offset:-1024 nt
	v_pk_mul_f32 v[84:85], v[110:111], v[144:145] op_sel_hi:[1,0]
	v_pk_mul_f32 v[86:87], v[108:109], v[144:145] op_sel_hi:[1,0]
	v_pk_fma_f32 v[78:79], v[198:199], v[84:85], v[78:79]
	v_pk_fma_f32 v[76:77], v[196:197], v[86:87], v[76:77]
	global_store_dwordx4 v[142:143], v[76:79], off nt
	v_pk_mul_f32 v[80:81], v[106:107], v[144:145] op_sel_hi:[1,0]
	v_pk_mul_f32 v[82:83], v[104:105], v[144:145] op_sel_hi:[1,0]
	v_pk_fma_f32 v[74:75], v[210:211], v[80:81], v[74:75]
	v_pk_fma_f32 v[72:73], v[208:209], v[82:83], v[72:73]
	global_store_dwordx4 v[142:143], v[72:75], off offset:1024 nt
	v_pk_mul_f32 v[76:77], v[98:99], v[144:145] op_sel_hi:[1,0]
	v_pk_mul_f32 v[78:79], v[96:97], v[144:145] op_sel_hi:[1,0]
	v_pk_fma_f32 v[70:71], v[76:77], v[214:215], v[70:71]
	v_pk_fma_f32 v[68:69], v[78:79], v[212:213], v[68:69]
	global_store_dwordx4 v[142:143], v[68:71], off offset:2048 nt
	v_pk_mul_f32 v[72:73], v[90:91], v[144:145] op_sel_hi:[1,0]
	v_pk_mul_f32 v[74:75], v[88:89], v[144:145] op_sel_hi:[1,0]
	v_pk_fma_f32 v[38:39], v[72:73], v[218:219], v[38:39]
	v_pk_fma_f32 v[36:37], v[74:75], v[216:217], v[36:37]
	global_store_dwordx4 v[142:143], v[36:39], off offset:3072 nt
	s_cbranch_vccnz .LBB0_1002
; DI void resnorm_rows(const float* Y, const float* Xs, float* Xd, const float* gpost, const float* gpre, bf16* H, int gw, int NGW, int lane) {
;     ...
;         if (!has) break;
; #pragma unroll
;         for (int j = 0; j < 8; ++j) { y[j] = yn[j]; x[j] = xn[j]; }
;         row = nrow;
	s_waitcnt vmcnt(8)
	v_readlane_b32 s4, v254, 50
	v_readlane_b32 s5, v254, 51
	s_add_i32 s0, s0, s62
	s_mov_b64 s[6:7], 0
	v_lshl_add_u64 v[142:143], v[142:143], 0, s[4:5]
	v_mov_b32_e32 v39, v63
	v_mov_b32_e32 v38, v62
	v_mov_b32_e32 v37, v61
	v_mov_b32_e32 v36, v60
	v_mov_b32_e32 v71, v67
	v_mov_b32_e32 v70, v66
	v_mov_b32_e32 v69, v65
	v_mov_b32_e32 v68, v64
	v_mov_b32_e32 v75, v55
	v_mov_b32_e32 v74, v54
	v_mov_b32_e32 v73, v53
	v_mov_b32_e32 v72, v52
	v_mov_b32_e32 v79, v59
	v_mov_b32_e32 v78, v58
	v_mov_b32_e32 v77, v57
	v_mov_b32_e32 v76, v56
	v_mov_b32_e32 v83, v27
	v_mov_b32_e32 v82, v26
	v_mov_b32_e32 v81, v25
	v_mov_b32_e32 v80, v24
	v_mov_b32_e32 v87, v31
	v_mov_b32_e32 v86, v30
	v_mov_b32_e32 v85, v29
	v_mov_b32_e32 v84, v28
	v_mov_b32_e32 v95, v19
	v_mov_b32_e32 v94, v18
	v_mov_b32_e32 v93, v17
	v_mov_b32_e32 v92, v16
	v_mov_b32_e32 v103, v23
	v_mov_b32_e32 v102, v22
	v_mov_b32_e32 v101, v21
	v_mov_b32_e32 v100, v20
	s_branch .LBB0_1002

; DI unsigned pk2(float lo, float hi) { f32x2_t v = {lo, hi}; bf16x2_t b = __builtin_convertvector(v, bf16x2_t); return __builtin_bit_cast(unsigned, b); }
; DI void resnorm_rows(const float* Y, const float* Xs, float* Xd, const float* gpost, const float* gpre, bf16* H, int gw, int NGW, int lane) {
;     int row = gw; if (row >= T) return;
;     f32x4 y[8], x[8], yn[8], xn[8];
;     { const f32x4* yr = (const f32x4*)(Y + (size_t)row * DM) + lane; const f32x4* xr = (const f32x4*)(Xs + (size_t)row * DM) + lane;
; #pragma unroll
;       for (int j = 0; j < 8; ++j) { y[j] = __builtin_nontemporal_load(yr + 64 * j); x[j] = __builtin_nontemporal_load(xr + 64 * j); } }
;     for (;;) {
;         const int nrow = row + NGW; const bool has = nrow < T;
;         if (has) { const f32x4* yr = (const f32x4*)(Y + (size_t)nrow * DM) + lane; const f32x4* xr = (const f32x4*)(Xs + (size_t)nrow * DM) + lane;
; #pragma unroll
;             for (int j = 0; j < 8; ++j) { yn[j] = __builtin_nontemporal_load(yr + 64 * j); xn[j] = __builtin_nontemporal_load(xr + 64 * j); } }
;     ...
;         for (int j = 0; j < 8; ++j) { const f32x4 gg = ((const f32x4*)gpost)[lane + 64 * j]; x[j] = x[j] + y[j] * r * gg; __builtin_nontemporal_store(x[j], xo + 64 * j);
;             s2 += (x[j].x * x[j].x + x[j].y * x[j].y) + (x[j].z * x[j].z + x[j].w * x[j].w); }
;         if (H) {
;             const float r2 = rsqrtf(wave_sum(s2) * (1.f / DM) + EPS);
;             u32x2* o = (u32x2*)(H + (size_t)row * DM) + lane;
; #pragma unroll
;             for (int j = 0; j < 8; ++j) { const f32x4 gg = ((const f32x4*)gpre)[lane + 64 * j]; u32x2 w; w.x = pk2(x[j].x * r2 * gg.x, x[j].y * r2 * gg.y); w.y = pk2(x[j].z * r2 * gg.z, x[j].w * r2 * gg.w); o[64 * j] = w; }
.LBB0_1009:
	s_mov_b32 s0, -1
	s_mov_b64 s[4:5], 0
	v_mbcnt_lo_u32_b32 v0, s0, 0
	v_mbcnt_hi_u32_b32 v0, s0, v0
	v_add_u32_e32 v0, s68, v0
	s_nop 0
	v_readfirstlane_b32 s0, v0
	s_ashr_i32 s6, s0, 6
	v_readlane_b32 s0, v252, 36
	s_add_i32 s0, s6, s0
	s_cmpk_gt_i32 s0, 0x3fff
	s_cbranch_scc1 .LBB0_1016
	v_readlane_b32 s12, v252, 20
	v_readlane_b32 s44, v252, 0
	s_lshl_b64 s[8:9], s[10:11], 2
	v_readlane_b32 s26, v252, 34
	v_mov_b64_e32 v[2:3], s[4:5]
	v_readlane_b32 s46, v252, 2
	v_readlane_b32 s47, v252, 3
	v_readlane_b32 s27, v252, 35
	s_add_u32 s8, s26, s8
	v_lshl_add_u64 v[2:3], s[46:47], 0, v[2:3]
	s_addc_u32 s9, s27, s9
	s_mov_b64 s[10:11], 0x17000000
	s_ashr_i32 s1, s0, 31
	v_lshl_add_u64 v[2:3], v[2:3], 0, s[10:11]
	v_and_b32_e32 v10, 63, v0
	s_lshl_b64 s[0:1], s[0:1], 13
	v_readlane_b32 s45, v252, 1
	v_lshl_add_u64 v[0:1], v[2:3], 0, s[0:1]
	v_lshlrev_b32_e32 v160, 4, v10
	s_add_u32 s0, s44, s0
	v_lshl_add_u64 v[0:1], v[0:1], 0, v[160:161]
	s_addc_u32 s1, s45, s1
	v_lshl_add_u64 v[4:5], s[0:1], 0, v[160:161]
	global_load_dwordx4 v[124:127], v[0:1], off nt
	global_load_dwordx4 v[120:123], v[0:1], off offset:1024 nt
	global_load_dwordx4 v[92:95], v160, s[0:1] nt
	global_load_dwordx4 v[88:91], v160, s[0:1] offset:1024 nt
	global_load_dwordx4 v[116:119], v[0:1], off offset:2048 nt
	global_load_dwordx4 v[112:115], v[0:1], off offset:3072 nt
	global_load_dwordx4 v[84:87], v160, s[0:1] offset:2048 nt
	global_load_dwordx4 v[80:83], v160, s[0:1] offset:3072 nt
	s_movk_i32 s0, 0x1000
	v_add_co_u32_e32 v0, vcc, s0, v0
	v_or_b32_e32 v8, 0x400, v160
	s_nop 0
	v_addc_co_u32_e32 v1, vcc, 0, v1, vcc
	v_add_co_u32_e32 v4, vcc, s0, v4
	v_readlane_b32 s0, v253, 36
	s_nop 0
	v_addc_co_u32_e32 v5, vcc, 0, v5, vcc
	global_load_dwordx4 v[108:111], v[0:1], off nt
	global_load_dwordx4 v[104:107], v[0:1], off offset:1024 nt
	global_load_dwordx4 v[76:79], v[4:5], off nt
	global_load_dwordx4 v[72:75], v[4:5], off offset:1024 nt
	global_load_dwordx4 v[100:103], v[0:1], off offset:2048 nt
	global_load_dwordx4 v[96:99], v[0:1], off offset:3072 nt
	global_load_dwordx4 v[68:71], v[4:5], off offset:2048 nt
	global_load_dwordx4 v[64:67], v[4:5], off offset:3072 nt
	v_readlane_b32 s1, v253, 37
	v_mov_b32_e32 v9, v161
	v_lshl_add_u64 v[128:129], v[2:3], 0, v[160:161]
	v_lshl_add_u64 v[144:145], s[0:1], 0, v[8:9]
	v_or_b32_e32 v8, 0x800, v160
	v_or_b32_e32 v0, 0x1000, v160
	v_mov_b32_e32 v1, v161
	v_or_b32_e32 v2, 0x1400, v160
	v_mov_b32_e32 v3, v161
	v_or_b32_e32 v4, 0x1800, v160
	v_mov_b32_e32 v5, v161
	v_or_b32_e32 v6, 0x1c00, v160
	v_mov_b32_e32 v7, v161
	v_lshl_add_u64 v[146:147], s[0:1], 0, v[8:9]
	v_or_b32_e32 v8, 0xc00, v160
	v_lshl_add_u64 v[142:143], s[0:1], 0, v[160:161]
	v_lshl_add_u64 v[148:149], s[0:1], 0, v[8:9]
	v_lshl_add_u64 v[150:151], s[0:1], 0, v[0:1]
	v_lshl_add_u64 v[152:153], s[0:1], 0, v[2:3]
	v_lshl_add_u64 v[154:155], s[0:1], 0, v[4:5]
	v_lshl_add_u64 v[156:157], s[0:1], 0, v[6:7]
	s_ashr_i32 s0, s6, 31
	v_readlane_b32 s1, v252, 36
	v_lshl_add_u64 v[132:133], s[8:9], 0, v[160:161]
	v_lshl_add_u64 v[134:135], s[8:9], 0, v[0:1]
	v_lshl_add_u64 v[136:137], s[8:9], 0, v[2:3]
	v_lshl_add_u64 v[138:139], s[8:9], 0, v[4:5]
	v_lshl_add_u64 v[140:141], s[8:9], 0, v[6:7]
	s_add_u32 s8, s1, s6
	v_readlane_b32 s1, v254, 48
	s_addc_u32 s9, s1, s0
	s_lshl_b64 s[0:1], s[8:9], 13
	v_readlane_b32 s7, v254, 44
	s_add_u32 s0, s7, s0
	v_readlane_b32 s7, v254, 45
	s_addc_u32 s1, s7, s1
	v_lshl_add_u64 v[158:159], s[0:1], 0, v[160:161]
	v_readlane_b32 s0, v254, 49
	s_add_i32 s0, s0, s6
	s_lshl_b64 s[6:7], s[8:9], 12
	v_mov_b64_e32 v[0:1], s[6:7]
	v_lshl_add_u64 v[130:131], s[44:45], 0, v[160:161]
	v_lshl_add_u64 v[0:1], s[4:5], 0, v[0:1]
	v_lshlrev_b32_e32 v160, 3, v10
	v_readlane_b32 s4, v254, 52
	v_lshl_add_u64 v[0:1], v[0:1], 0, v[160:161]
	v_readlane_b32 s5, v254, 53
	v_readlane_b32 s13, v252, 21
	v_readlane_b32 s14, v252, 22
	v_lshl_add_u64 v[170:171], s[4:5], 0, v[0:1]
	v_readlane_b32 s15, v252, 23
	v_readlane_b32 s16, v252, 24
	v_readlane_b32 s17, v252, 25
	v_readlane_b32 s18, v252, 26
	v_readlane_b32 s19, v252, 27
	v_readlane_b32 s20, v252, 28
	v_readlane_b32 s21, v252, 29
	v_readlane_b32 s22, v252, 30
	v_readlane_b32 s23, v252, 31
	v_readlane_b32 s24, v252, 32
	v_readlane_b32 s25, v252, 33
	global_load_dwordx4 v[180:183], v[132:133], off
	global_load_dwordx4 v[184:187], v[132:133], off offset:1024
	global_load_dwordx4 v[188:191], v[132:133], off offset:2048
	global_load_dwordx4 v[192:195], v[132:133], off offset:3072
	global_load_dwordx4 v[196:199], v[134:135], off
	global_load_dwordx4 v[208:211], v[136:137], off
	global_load_dwordx4 v[212:215], v[138:139], off
	global_load_dwordx4 v[216:219], v[140:141], off
	global_load_dwordx4 v[220:223], v[142:143], off
	global_load_dwordx4 v[224:227], v[144:145], off
	global_load_dwordx4 v[228:231], v[146:147], off
	global_load_dwordx4 v[232:235], v[148:149], off
	global_load_dwordx4 v[236:239], v[150:151], off
	global_load_dwordx4 v[240:243], v[152:153], off
	global_load_dwordx4 v[244:247], v[154:155], off
	global_load_dwordx4 v[248:251], v[156:157], off
	s_waitcnt vmcnt(0)
	s_branch .LBB0_1012

; DI void resnorm_rows(const float* Y, const float* Xs, float* Xd, const float* gpost, const float* gpre, bf16* H, int gw, int NGW, int lane) {
;     ...
;         float ss = 0.f;
; #pragma unroll
;         for (int j = 0; j < 8; ++j) ss += (y[j].x * y[j].x + y[j].y * y[j].y) + (y[j].z * y[j].z + y[j].w * y[j].w);
;         const float r = rsqrtf(wave_sum(ss) * (1.f / DM) + EPS);
;         f32x4* xo = (f32x4*)(Xd + (size_t)row * DM) + lane; float s2 = 0.f;
; #pragma unroll
;         for (int j = 0; j < 8; ++j) { const f32x4 gg = ((const f32x4*)gpost)[lane + 64 * j]; x[j] = x[j] + y[j] * r * gg; __builtin_nontemporal_store(x[j], xo + 64 * j);
;             s2 += (x[j].x * x[j].x + x[j].y * x[j].y) + (x[j].z * x[j].z + x[j].w * x[j].w); }
.LBB0_1014:
	v_mov_b32_e32 v174, v121
	v_mov_b32_e32 v175, v125
	v_mov_b32_e32 v172, v120
	v_mov_b32_e32 v173, v124
	v_pk_mul_f32 v[174:175], v[174:175], v[174:175]
	v_mov_b32_e32 v176, v123
	v_mov_b32_e32 v177, v127
	v_pk_fma_f32 v[172:173], v[172:173], v[172:173], v[174:175]
	v_mov_b32_e32 v174, v122
	v_mov_b32_e32 v175, v126
	v_pk_mul_f32 v[176:177], v[176:177], v[176:177]
	v_mul_f32_e32 v160, v112, v112
	v_pk_fma_f32 v[174:175], v[174:175], v[174:175], v[176:177]
	v_pk_mul_f32 v[176:177], v[116:117], v[116:117]
	v_pk_add_f32 v[172:173], v[172:173], v[174:175]
	v_pk_mul_f32 v[174:175], v[118:119], v[118:119]
	v_pk_add_f32 v[172:173], v[172:173], v[172:173] op_sel_hi:[0,1]
	v_pk_mov_b32 v[178:179], v[176:177], v[174:175] op_sel:[1,0]
	v_mov_b32_e32 v177, v175
	v_pk_add_f32 v[174:175], v[178:179], v[176:177]
	v_pk_fma_f32 v[176:177], v[112:113], v[112:113], v[160:161] op_sel_hi:[1,1,0]
	v_mul_f32_e32 v160, v114, v114
	v_pk_add_f32 v[174:175], v[174:175], v[174:175] op_sel_hi:[0,1]
	v_pk_fma_f32 v[178:179], v[114:115], v[114:115], v[160:161] op_sel_hi:[1,1,0]
	v_mul_f32_e32 v176, v108, v108
	v_mul_f32_e32 v178, v109, v109
	v_mul_f32_e32 v174, v110, v110
	v_mul_f32_e32 v172, v111, v111
	v_pk_add_f32 v[176:177], v[176:177], v[178:179]
	v_pk_add_f32 v[172:173], v[174:175], v[172:173]
	v_pk_mul_f32 v[174:175], v[106:107], v[106:107]
	v_pk_add_f32 v[172:173], v[176:177], v[172:173]
	v_pk_mul_f32 v[176:177], v[104:105], v[104:105]
	v_mul_f32_e32 v160, v100, v100
	v_pk_mov_b32 v[178:179], v[176:177], v[174:175] op_sel:[1,0]
	v_mov_b32_e32 v177, v175
	v_pk_add_f32 v[174:175], v[178:179], v[176:177]
	v_pk_fma_f32 v[176:177], v[100:101], v[100:101], v[160:161] op_sel_hi:[1,1,0]
	v_mul_f32_e32 v160, v102, v102
	v_pk_add_f32 v[172:173], v[172:173], v[172:173] op_sel_hi:[0,1]
	v_pk_add_f32 v[174:175], v[174:175], v[174:175] op_sel_hi:[0,1]
	v_pk_fma_f32 v[178:179], v[102:103], v[102:103], v[160:161] op_sel_hi:[1,1,0]
	v_mul_f32_e32 v176, v96, v96
	v_mul_f32_e32 v178, v97, v97
	v_mul_f32_e32 v174, v98, v98
	v_mul_f32_e32 v172, v99, v99
	v_pk_add_f32 v[176:177], v[176:177], v[178:179]
	v_pk_add_f32 v[172:173], v[174:175], v[172:173]
	s_mov_b32 s1, -1
	v_pk_add_f32 v[172:173], v[176:177], v[172:173]
	s_mov_b64 s[6:7], -1
	v_add_f32_e32 v160, v172, v173
	v_mbcnt_lo_u32_b32 v172, s1, 0
	v_mbcnt_hi_u32_b32 v172, s1, v172
	v_lshlrev_b32_e32 v172, 2, v172
	v_xor_b32_e32 v172, 4, v172
	ds_bpermute_b32 v172, v172, v160
	s_mov_b32 s1, -1
	s_waitcnt lgkmcnt(0)
	v_add_f32_e32 v160, v160, v172
	v_mbcnt_lo_u32_b32 v172, s1, 0
	v_mbcnt_hi_u32_b32 v172, s1, v172
	v_lshlrev_b32_e32 v172, 2, v172
	v_xor_b32_e32 v172, 8, v172
	ds_bpermute_b32 v172, v172, v160
	s_mov_b32 s1, -1
	s_waitcnt lgkmcnt(0)
	v_add_f32_e32 v160, v160, v172
	v_mbcnt_lo_u32_b32 v172, s1, 0
	v_mbcnt_hi_u32_b32 v172, s1, v172
	v_lshlrev_b32_e32 v172, 2, v172
	v_xor_b32_e32 v172, 16, v172
	ds_bpermute_b32 v172, v172, v160
	s_mov_b32 s1, -1
	s_waitcnt lgkmcnt(0)
	v_add_f32_e32 v160, v160, v172
	v_mbcnt_lo_u32_b32 v172, s1, 0
	v_mbcnt_hi_u32_b32 v172, s1, v172
	v_lshlrev_b32_e32 v172, 2, v172
	v_xor_b32_e32 v172, 32, v172
	ds_bpermute_b32 v172, v172, v160
	s_mov_b32 s1, -1
	s_waitcnt lgkmcnt(0)
	v_add_f32_e32 v160, v160, v172
	v_mbcnt_lo_u32_b32 v172, s1, 0
	v_mbcnt_hi_u32_b32 v172, s1, v172
	v_lshlrev_b32_e32 v172, 2, v172
	v_xor_b32_e32 v172, 64, v172
	ds_bpermute_b32 v172, v172, v160
	s_mov_b32 s1, -1
	s_waitcnt lgkmcnt(0)
	v_add_f32_e32 v160, v160, v172
	v_mbcnt_lo_u32_b32 v172, s1, 0
	v_mbcnt_hi_u32_b32 v172, s1, v172
	v_lshlrev_b32_e32 v172, 2, v172
	v_xor_b32_e32 v172, 0x80, v172
	ds_bpermute_b32 v172, v172, v160
	s_mov_b32 s1, -1
	s_waitcnt lgkmcnt(0)
	v_add_f32_e32 v160, v160, v172
	v_fmamk_f32 v160, v160, 0x3a000000, v203
	v_cmp_gt_f32_e32 vcc, s2, v160
	v_mul_f32_e32 v172, 0x4b800000, v160
	s_nop 0
	v_cndmask_b32_e32 v160, v160, v172, vcc
	v_rsq_f32_e32 v160, v160
	s_nop 0
	v_mul_f32_e32 v172, 0x45800000, v160
	v_cndmask_b32_e32 v160, v160, v172, vcc
	v_pk_mul_f32 v[124:125], v[124:125], v[160:161] op_sel_hi:[1,0]
	v_pk_mul_f32 v[126:127], v[126:127], v[160:161] op_sel_hi:[1,0]
	v_pk_mul_f32 v[122:123], v[122:123], v[160:161] op_sel_hi:[1,0]
	v_pk_mul_f32 v[120:121], v[120:121], v[160:161] op_sel_hi:[1,0]
	v_pk_mul_f32 v[118:119], v[118:119], v[160:161] op_sel_hi:[1,0]
	v_pk_mul_f32 v[116:117], v[116:117], v[160:161] op_sel_hi:[1,0]
	v_pk_mul_f32 v[114:115], v[114:115], v[160:161] op_sel_hi:[1,0]
	v_pk_mul_f32 v[112:113], v[112:113], v[160:161] op_sel_hi:[1,0]
	v_pk_mul_f32 v[108:109], v[108:109], v[160:161] op_sel_hi:[1,0]
	v_pk_mul_f32 v[110:111], v[110:111], v[160:161] op_sel_hi:[1,0]
	v_pk_mul_f32 v[106:107], v[106:107], v[160:161] op_sel_hi:[1,0]
	v_pk_mul_f32 v[104:105], v[104:105], v[160:161] op_sel_hi:[1,0]
	v_pk_mul_f32 v[102:103], v[102:103], v[160:161] op_sel_hi:[1,0]
	v_pk_mul_f32 v[100:101], v[100:101], v[160:161] op_sel_hi:[1,0]
	v_pk_mul_f32 v[98:99], v[98:99], v[160:161] op_sel_hi:[1,0]
	v_pk_mul_f32 v[96:97], v[96:97], v[160:161] op_sel_hi:[1,0]
	v_pk_fma_f32 v[94:95], v[182:183], v[126:127], v[94:95]
	v_pk_fma_f32 v[92:93], v[180:181], v[124:125], v[92:93]
	global_store_dwordx4 v[158:159], v[92:95], off offset:-4096 nt
	v_pk_fma_f32 v[88:89], v[184:185], v[120:121], v[88:89]
	v_pk_fma_f32 v[90:91], v[186:187], v[122:123], v[90:91]
	global_store_dwordx4 v[158:159], v[88:91], off offset:-3072 nt
	v_pk_fma_f32 v[84:85], v[188:189], v[116:117], v[84:85]
	v_pk_fma_f32 v[86:87], v[190:191], v[118:119], v[86:87]
	global_store_dwordx4 v[158:159], v[84:87], off offset:-2048 nt
	v_pk_fma_f32 v[80:81], v[192:193], v[112:113], v[80:81]
	v_pk_fma_f32 v[82:83], v[194:195], v[114:115], v[82:83]
; DI void resnorm_rows(const float* Y, const float* Xs, float* Xd, const float* gpost, const float* gpre, bf16* H, int gw, int NGW, int lane) {
;     ...
;         for (int j = 0; j < 8; ++j) { const f32x4 gg = ((const f32x4*)gpost)[lane + 64 * j]; x[j] = x[j] + y[j] * r * gg; __builtin_nontemporal_store(x[j], xo + 64 * j);
;             s2 += (x[j].x * x[j].x + x[j].y * x[j].y) + (x[j].z * x[j].z + x[j].w * x[j].w); }
;         if (H) {
;             const float r2 = rsqrtf(wave_sum(s2) * (1.f / DM) + EPS);
	global_store_dwordx4 v[158:159], v[80:83], off offset:-1024 nt
	v_pk_fma_f32 v[78:79], v[198:199], v[110:111], v[78:79]
	v_pk_fma_f32 v[76:77], v[196:197], v[108:109], v[76:77]
	global_store_dwordx4 v[158:159], v[76:79], off nt
	v_pk_fma_f32 v[72:73], v[208:209], v[104:105], v[72:73]
	v_pk_fma_f32 v[74:75], v[210:211], v[106:107], v[74:75]
	global_store_dwordx4 v[158:159], v[72:75], off offset:1024 nt
	v_pk_fma_f32 v[68:69], v[100:101], v[212:213], v[68:69]
	v_pk_fma_f32 v[70:71], v[102:103], v[214:215], v[70:71]
	global_store_dwordx4 v[158:159], v[68:71], off offset:2048 nt
	v_pk_fma_f32 v[66:67], v[98:99], v[218:219], v[66:67]
	v_mov_b32_e32 v98, v93
	v_mov_b32_e32 v99, v89
	v_pk_fma_f32 v[64:65], v[96:97], v[216:217], v[64:65]
	v_mov_b32_e32 v96, v92
	v_mov_b32_e32 v97, v88
	v_pk_mul_f32 v[98:99], v[98:99], v[98:99]
	v_mov_b32_e32 v100, v95
	v_mov_b32_e32 v101, v91
	v_pk_fma_f32 v[96:97], v[96:97], v[96:97], v[98:99]
	v_mov_b32_e32 v98, v94
	v_mov_b32_e32 v99, v90
	v_pk_mul_f32 v[100:101], v[100:101], v[100:101]
	global_store_dwordx4 v[158:159], v[64:67], off offset:3072 nt
	v_pk_fma_f32 v[98:99], v[98:99], v[98:99], v[100:101]
	v_pk_mul_f32 v[100:101], v[86:87], v[86:87]
	v_pk_add_f32 v[96:97], v[96:97], v[98:99]
	v_pk_mul_f32 v[98:99], v[84:85], v[84:85]
	v_pk_add_f32 v[96:97], v[96:97], v[96:97] op_sel_hi:[0,1]
	v_pk_mov_b32 v[102:103], v[98:99], v[100:101] op_sel:[1,0]
	v_mov_b32_e32 v99, v101
	v_mul_f32_e32 v96, v80, v80
	v_pk_add_f32 v[98:99], v[102:103], v[98:99]
	v_pk_fma_f32 v[100:101], v[80:81], v[80:81], v[96:97] op_sel_hi:[1,1,0]
	v_mul_f32_e32 v96, v82, v82
	v_pk_add_f32 v[98:99], v[98:99], v[98:99] op_sel_hi:[0,1]
	v_pk_fma_f32 v[102:103], v[82:83], v[82:83], v[96:97] op_sel_hi:[1,1,0]
	v_mul_f32_e32 v100, v76, v76
	v_mul_f32_e32 v102, v77, v77
	v_mul_f32_e32 v98, v78, v78
	v_mul_f32_e32 v96, v79, v79
	v_pk_add_f32 v[100:101], v[100:101], v[102:103]
	v_pk_add_f32 v[96:97], v[98:99], v[96:97]
	v_pk_mul_f32 v[98:99], v[72:73], v[72:73]
	v_pk_add_f32 v[96:97], v[100:101], v[96:97]
	v_pk_mul_f32 v[100:101], v[74:75], v[74:75]
	v_pk_add_f32 v[96:97], v[96:97], v[96:97] op_sel_hi:[0,1]
	v_pk_mov_b32 v[102:103], v[98:99], v[100:101] op_sel:[1,0]
	v_mov_b32_e32 v99, v101
	v_mul_f32_e32 v96, v68, v68
	v_pk_add_f32 v[98:99], v[102:103], v[98:99]
	v_pk_fma_f32 v[100:101], v[68:69], v[68:69], v[96:97] op_sel_hi:[1,1,0]
	v_mul_f32_e32 v96, v70, v70
	v_pk_add_f32 v[98:99], v[98:99], v[98:99] op_sel_hi:[0,1]
	v_pk_fma_f32 v[102:103], v[70:71], v[70:71], v[96:97] op_sel_hi:[1,1,0]
	v_mul_f32_e32 v100, v64, v64
	v_mul_f32_e32 v102, v65, v65
	v_mul_f32_e32 v98, v66, v66
	v_mul_f32_e32 v96, v67, v67
	v_pk_add_f32 v[100:101], v[100:101], v[102:103]
	v_pk_add_f32 v[96:97], v[98:99], v[96:97]
	s_nop 0
	v_pk_add_f32 v[96:97], v[100:101], v[96:97]
	s_nop 0
	v_add_f32_e32 v96, v96, v97
	v_mbcnt_lo_u32_b32 v97, s1, 0
	v_mbcnt_hi_u32_b32 v97, s1, v97
	v_lshlrev_b32_e32 v97, 2, v97
	v_xor_b32_e32 v97, 4, v97
	ds_bpermute_b32 v97, v97, v96
	s_mov_b32 s1, -1
	s_waitcnt lgkmcnt(0)
	v_add_f32_e32 v96, v96, v97
	v_mbcnt_lo_u32_b32 v97, s1, 0
	v_mbcnt_hi_u32_b32 v97, s1, v97
	v_lshlrev_b32_e32 v97, 2, v97
	v_xor_b32_e32 v97, 8, v97
	ds_bpermute_b32 v97, v97, v96
	s_mov_b32 s1, -1
	s_waitcnt lgkmcnt(0)
	v_add_f32_e32 v96, v96, v97
	v_mbcnt_lo_u32_b32 v97, s1, 0
	v_mbcnt_hi_u32_b32 v97, s1, v97
	v_lshlrev_b32_e32 v97, 2, v97
	v_xor_b32_e32 v97, 16, v97
	ds_bpermute_b32 v97, v97, v96
	s_mov_b32 s1, -1
	s_waitcnt lgkmcnt(0)
	v_add_f32_e32 v96, v96, v97
	v_mbcnt_lo_u32_b32 v97, s1, 0
	v_mbcnt_hi_u32_b32 v97, s1, v97
	v_lshlrev_b32_e32 v97, 2, v97
	v_xor_b32_e32 v97, 32, v97
	ds_bpermute_b32 v97, v97, v96
	s_mov_b32 s1, -1
	s_waitcnt lgkmcnt(0)
	v_add_f32_e32 v96, v96, v97
	v_mbcnt_lo_u32_b32 v97, s1, 0
	v_mbcnt_hi_u32_b32 v97, s1, v97
	v_lshlrev_b32_e32 v97, 2, v97
	v_xor_b32_e32 v97, 64, v97
	ds_bpermute_b32 v97, v97, v96
	s_mov_b32 s1, -1
	s_waitcnt lgkmcnt(0)
	v_add_f32_e32 v96, v96, v97
	v_mbcnt_lo_u32_b32 v97, s1, 0
	v_mbcnt_hi_u32_b32 v97, s1, v97
	v_lshlrev_b32_e32 v97, 2, v97
	v_xor_b32_e32 v97, 0x80, v97
	ds_bpermute_b32 v97, v97, v96
	s_waitcnt lgkmcnt(0)
; DI unsigned pk2(float lo, float hi) { f32x2_t v = {lo, hi}; bf16x2_t b = __builtin_convertvector(v, bf16x2_t); return __builtin_bit_cast(unsigned, b); }
; DI void resnorm_rows(const float* Y, const float* Xs, float* Xd, const float* gpost, const float* gpre, bf16* H, int gw, int NGW, int lane) {
;     ...
;             const float r2 = rsqrtf(wave_sum(s2) * (1.f / DM) + EPS);
;             u32x2* o = (u32x2*)(H + (size_t)row * DM) + lane;
; #pragma unroll
;             for (int j = 0; j < 8; ++j) { const f32x4 gg = ((const f32x4*)gpre)[lane + 64 * j]; u32x2 w; w.x = pk2(x[j].x * r2 * gg.x, x[j].y * r2 * gg.y); w.y = pk2(x[j].z * r2 * gg.z, x[j].w * r2 * gg.w); o[64 * j] = w; }
;         }
;         if (!has) break;
; #pragma unroll
;         for (int j = 0; j < 8; ++j) { y[j] = yn[j]; x[j] = xn[j]; }
;         row = nrow;
	v_add_f32_e32 v96, v96, v97
	v_fmamk_f32 v96, v96, 0x3a000000, v203
	v_cmp_gt_f32_e32 vcc, s2, v96
	v_mul_f32_e32 v97, 0x4b800000, v96
	s_nop 0
	v_cndmask_b32_e32 v96, v96, v97, vcc
	v_rsq_f32_e32 v96, v96
	s_nop 0
	v_mul_f32_e32 v97, 0x45800000, v96
	v_cndmask_b32_e32 v100, v96, v97, vcc
	v_pk_mul_f32 v[92:93], v[92:93], v[100:101] op_sel_hi:[1,0]
	v_pk_mul_f32 v[94:95], v[94:95], v[100:101] op_sel_hi:[1,0]
	v_pk_mul_f32 v[88:89], v[88:89], v[100:101] op_sel_hi:[1,0]
	v_pk_mul_f32 v[90:91], v[90:91], v[100:101] op_sel_hi:[1,0]
	v_pk_mul_f32 v[84:85], v[84:85], v[100:101] op_sel_hi:[1,0]
	v_pk_mul_f32 v[86:87], v[86:87], v[100:101] op_sel_hi:[1,0]
	v_pk_mul_f32 v[80:81], v[80:81], v[100:101] op_sel_hi:[1,0]
	v_pk_mul_f32 v[82:83], v[82:83], v[100:101] op_sel_hi:[1,0]
	v_pk_mul_f32 v[76:77], v[76:77], v[100:101] op_sel_hi:[1,0]
	v_pk_mul_f32 v[78:79], v[78:79], v[100:101] op_sel_hi:[1,0]
	v_pk_mul_f32 v[72:73], v[72:73], v[100:101] op_sel_hi:[1,0]
	v_pk_mul_f32 v[74:75], v[74:75], v[100:101] op_sel_hi:[1,0]
	v_pk_mul_f32 v[68:69], v[68:69], v[100:101] op_sel_hi:[1,0]
	v_pk_mul_f32 v[70:71], v[70:71], v[100:101] op_sel_hi:[1,0]
	v_pk_mul_f32 v[64:65], v[64:65], v[100:101] op_sel_hi:[1,0]
	v_pk_mul_f32 v[66:67], v[66:67], v[100:101] op_sel_hi:[1,0]
	s_andn2_b64 vcc, exec, s[4:5]
	v_pk_mul_f32 v[92:93], v[220:221], v[92:93]
	v_pk_mul_f32 v[94:95], v[222:223], v[94:95]
	v_cvt_pk_bf16_f32 v92, v92, v93
	v_cvt_pk_bf16_f32 v93, v94, v95
	global_store_dwordx2 v[170:171], v[92:93], off offset:-2048
	v_pk_mul_f32 v[88:89], v[224:225], v[88:89]
	v_pk_mul_f32 v[90:91], v[226:227], v[90:91]
	v_cvt_pk_bf16_f32 v88, v88, v89
	v_cvt_pk_bf16_f32 v89, v90, v91
	global_store_dwordx2 v[170:171], v[88:89], off offset:-1536
	v_pk_mul_f32 v[84:85], v[228:229], v[84:85]
	v_pk_mul_f32 v[86:87], v[230:231], v[86:87]
	v_cvt_pk_bf16_f32 v84, v84, v85
	v_cvt_pk_bf16_f32 v85, v86, v87
	global_store_dwordx2 v[170:171], v[84:85], off offset:-1024
	v_pk_mul_f32 v[80:81], v[232:233], v[80:81]
	v_pk_mul_f32 v[82:83], v[234:235], v[82:83]
	v_cvt_pk_bf16_f32 v80, v80, v81
	v_cvt_pk_bf16_f32 v81, v82, v83
	global_store_dwordx2 v[170:171], v[80:81], off offset:-512
	v_pk_mul_f32 v[76:77], v[76:77], v[236:237]
	v_pk_mul_f32 v[78:79], v[78:79], v[238:239]
	v_cvt_pk_bf16_f32 v76, v76, v77
	v_cvt_pk_bf16_f32 v77, v78, v79
	global_store_dwordx2 v[170:171], v[76:77], off
	v_pk_mul_f32 v[72:73], v[72:73], v[240:241]
	v_pk_mul_f32 v[74:75], v[74:75], v[242:243]
	v_cvt_pk_bf16_f32 v72, v72, v73
	v_cvt_pk_bf16_f32 v73, v74, v75
	global_store_dwordx2 v[170:171], v[72:73], off offset:512
	v_pk_mul_f32 v[68:69], v[68:69], v[244:245]
	v_pk_mul_f32 v[70:71], v[70:71], v[246:247]
	v_cvt_pk_bf16_f32 v68, v68, v69
	v_cvt_pk_bf16_f32 v69, v70, v71
	global_store_dwordx2 v[170:171], v[68:69], off offset:1024
	v_pk_mul_f32 v[64:65], v[64:65], v[248:249]
	v_pk_mul_f32 v[66:67], v[66:67], v[250:251]
	v_cvt_pk_bf16_f32 v64, v64, v65
	v_cvt_pk_bf16_f32 v65, v66, v67
	global_store_dwordx2 v[170:171], v[64:65], off offset:1536
	s_cbranch_vccnz .LBB0_1011
	s_waitcnt vmcnt(16)
	v_readlane_b32 s4, v254, 50
	v_readlane_b32 s5, v254, 51
	s_add_i32 s0, s0, s62
	s_mov_b64 s[6:7], 0
	v_lshl_add_u64 v[158:159], v[158:159], 0, s[4:5]
	v_readlane_b32 s4, v254, 54
	v_readlane_b32 s5, v254, 55
	v_mov_b32_e32 v67, v59
	v_mov_b32_e32 v66, v58
	v_lshl_add_u64 v[170:171], v[170:171], 0, s[4:5]
	v_mov_b32_e32 v65, v57
	v_mov_b32_e32 v64, v56
	v_mov_b32_e32 v71, v63
	v_mov_b32_e32 v70, v62
	v_mov_b32_e32 v69, v61
	v_mov_b32_e32 v68, v60
	v_mov_b32_e32 v75, v51
	v_mov_b32_e32 v74, v50
	v_mov_b32_e32 v73, v49
	v_mov_b32_e32 v72, v48
	v_mov_b32_e32 v79, v55
	v_mov_b32_e32 v78, v54
	v_mov_b32_e32 v77, v53
	v_mov_b32_e32 v76, v52
	v_mov_b32_e32 v83, v27
	v_mov_b32_e32 v82, v26
	v_mov_b32_e32 v81, v25
	v_mov_b32_e32 v80, v24
	v_mov_b32_e32 v87, v31
	v_mov_b32_e32 v86, v30
	v_mov_b32_e32 v85, v29
	v_mov_b32_e32 v84, v28
	v_mov_b32_e32 v91, v19
	v_mov_b32_e32 v90, v18
	v_mov_b32_e32 v89, v17
	v_mov_b32_e32 v88, v16
	v_mov_b32_e32 v95, v23
	v_mov_b32_e32 v94, v22
	v_mov_b32_e32 v93, v21
	v_mov_b32_e32 v92, v20
	s_branch .LBB0_1011
